# S5: per-step in-place operand reload (no load burst, no copies), uniform vmcnt(11)
# speedup vs baseline: 1.0226x; 1.0130x over previous
; DI unsigned pack2(float a, float b) { f32x2_t v = {a, b}; bf16x2_t r = __builtin_convertvector(v, bf16x2_t); return __builtin_bit_cast(unsigned, r); }
; DI float sigmoidf_(float x) { return 1.f / (1.f + __expf(-x)); }
; DI bfu* wsb(const PX& p, size_t off) { return (bfu*)(p.ws + off); }
; DI void kstage4(const PX& p, const bfu* __restrict__ A, const bfu* __restrict__ Bt, const int K, const int brow, const int bcol, bfu* shm) {
;     ...
;   unsigned oa0, oa1, obb0, obb1;
;   { int r_, c_;
;     stage_rc(tid * 16, r_, c_); oa0 = (unsigned)(r_ * K + c_) * 2u;
;     { const int rho = r_ & 31, pr = (r_ & ~31) + 8 * ((rho & 15) >> 2) + 4 * (rho >> 4) + (rho & 3); obb0 = (unsigned)(pr * K + c_) * 2u; }
;     stage_rc(tid * 16 + 8192, r_, c_); oa1 = (unsigned)(r_ * K + c_) * 2u;
;     { const int rho = r_ & 31, pr = (r_ & ~31) + 8 * ((rho & 15) >> 2) + 4 * (rho >> 4) + (rho & 3); obb1 = (unsigned)(pr * K + c_) * 2u; } }
;     ...
;   KS_(shm + 4 * HT, Bt, bcol, obb0, obb1);
;   KS_(shm + 0 * HT, A, brow, oa0, oa1);
;   KS_(shm + 5 * HT, Bt, bcol + HALF, obb0, obb1);
;   KS_(shm + 1 * HT, A, brow + HALF, oa0, oa1);
; template <int EPI, int HM>
; DI void epi256(const PX& p, int l, f32x4 (&acc)[2][2][4][2], int brow, int bcol, int aux, bool src_input) {
;     ...
;           } else if (EPI == EPI_GATE) {
;             uint4 o;
;             o.x = pack2(sigmoidf_(v[0]), sigmoidf_(v[1])); o.y = pack2(sigmoidf_(v[2]), sigmoidf_(v[3]));
;             o.z = pack2(sigmoidf_(v[4]), sigmoidf_(v[5])); o.w = pack2(sigmoidf_(v[6]), sigmoidf_(v[7]));
;             *(uint4*)(wsb(p, OFF_BIG + B_ZML) + (size_t)row * 2048 + col0) = o;
.LBB0_267:
	s_or_b64 exec, exec, s[24:25]
	v_mov_b32_e32 v0, v188
	s_cmp_eq_u32 s7, 1
	v_ashrrev_i32_e32 v67, 31, v0
	v_lshrrev_b32_e32 v67, 26, v67
	v_lshlrev_b32_e32 v66, 4, v0
	v_add_u32_e32 v67, v0, v67
	v_bfe_i32 v0, v0, 27, 1
	v_lshrrev_b32_e32 v0, 22, v0
	v_add_u32_e32 v0, v66, v0
	v_and_b32_e32 v0, 0xfffffc00, v0
	v_sub_u32_e32 v0, v66, v0
	s_mov_b32 s12, 0x2f618100
	v_lshrrev_b32_e32 v68, 4, v0
	s_cselect_b32 s24, s12, 0x39818100
	s_mov_b32 s12, 0x1d88000
	v_bitop3_b32 v0, v68, v0, 32 bitop3:0x6c
	s_cselect_b32 s25, s12, 0x1f08000
	s_and_b64 s[12:13], s[4:5], exec
	v_ashrrev_i32_e32 v69, 31, v0
	s_cselect_b32 s73, 0x2c018100, s24
	v_ashrrev_i32_e32 v67, 6, v67
	v_lshrrev_b32_e32 v69, 26, v69
	s_add_u32 s13, s96, s73
	v_lshlrev_b32_e32 v68, 3, v67
	v_add_u32_e32 v69, v0, v69
	s_addc_u32 s62, s97, 0
	v_and_b32_e32 v68, -16, v68
	v_ashrrev_i32_e32 v70, 6, v69
	v_and_b32_e32 v69, 0xc0, v69
	s_and_b64 s[4:5], s[4:5], exec
	v_add_u32_e32 v68, v70, v68
	v_lshlrev_b32_e32 v67, 5, v67
	v_sub_u32_e32 v0, v0, v69
	s_cselect_b32 s4, 0x1c08000, s25
	v_and_b32_e32 v67, 32, v67
	v_ashrrev_i16_sdwa v0, v210, sext(v0) dst_sel:DWORD dst_unused:UNUSED_PAD src0_sel:DWORD src1_sel:BYTE_0
	s_movk_i32 s24, 0x300
	v_lshlrev_b32_e32 v69, 1, v68
	v_lshrrev_b32_e32 v71, 2, v68
	v_and_b32_e32 v70, 3, v70
	s_mov_b32 s25, 0xffffe0
	v_add_u32_sdwa v0, v67, sext(v0) dst_sel:DWORD dst_unused:UNUSED_PAD src0_sel:DWORD src1_sel:WORD_0
	v_mul_lo_u32 v67, v68, s24
	v_and_b32_e32 v69, 24, v69
	v_and_b32_e32 v71, 4, v71
	v_and_or_b32 v68, v68, s25, v70
	v_or3_b32 v68, v68, v69, v71
	v_mul_u32_u24_e32 v68, 0x300, v68
	v_add_u32_e32 v66, 0x2000, v66
	v_add_lshl_u32 v67, v0, v67, 1
	v_add_lshl_u32 v0, v68, v0, 1
	v_ashrrev_i32_e32 v68, 31, v66
	v_lshrrev_b32_e32 v68, 22, v68
	v_add_u32_e32 v68, v66, v68
	v_ashrrev_i32_e32 v68, 10, v68
	v_mul_i32_i24_e32 v69, 0x400, v68
	v_sub_u32_e32 v66, v66, v69
	v_lshrrev_b32_e32 v69, 4, v66
	v_bitop3_b32 v66, v69, v66, 32 bitop3:0x6c
	v_ashrrev_i32_e32 v70, 31, v66
	v_lshrrev_b32_e32 v70, 26, v70
	v_lshlrev_b32_e32 v69, 3, v68
	v_add_u32_e32 v70, v66, v70
	v_and_b32_e32 v69, -16, v69
	v_ashrrev_i32_e32 v71, 6, v70
	v_and_b32_e32 v70, 0xc0, v70
	s_lshl_b32 s12, s4, 1
	v_add_u32_e32 v69, v71, v69
	v_lshlrev_b32_e32 v68, 5, v68
	v_sub_u32_e32 v66, v66, v70
	s_add_u32 s4, s96, s12
	v_and_b32_e32 v68, 32, v68
	v_ashrrev_i16_sdwa v66, v210, sext(v66) dst_sel:DWORD dst_unused:UNUSED_PAD src0_sel:DWORD src1_sel:BYTE_0
	v_lshlrev_b32_e32 v70, 1, v69
	v_lshrrev_b32_e32 v72, 2, v69
	v_and_b32_e32 v71, 3, v71
	s_addc_u32 s5, s97, 0
	v_add_u32_sdwa v66, v68, sext(v66) dst_sel:DWORD dst_unused:UNUSED_PAD src0_sel:DWORD src1_sel:WORD_0
	v_mul_lo_u32 v68, v69, s24
	v_and_b32_e32 v70, 24, v70
	v_and_b32_e32 v72, 4, v72
	v_and_or_b32 v69, v69, s25, v71
	v_readlane_b32 s36, v253, 31
	v_or3_b32 v69, v69, v70, v72
	s_add_u32 s24, s4, s68
	s_mul_hi_u32 s25, s36, 0x600
	v_mul_u32_u24_e32 v69, 0x300, v69
	s_addc_u32 s25, s5, s25
	s_mov_b32 m0, s33
	s_mul_i32 s26, s6, 0x600
	v_add_lshl_u32 v68, v66, v68, 1
	v_add_lshl_u32 v66, v69, v66, 1
	global_load_lds_dwordx4 v0, s[24:25]
	s_mov_b32 m0, s64
	s_add_u32 s26, s13, s26
	global_load_lds_dwordx4 v66, s[24:25]
	s_addc_u32 s27, s62, 0
	s_mov_b32 m0, s82
	s_add_u32 s60, s4, s70
	global_load_lds_dwordx4 v67, s[26:27]
	s_mov_b32 m0, s77
	s_addc_u32 s61, s5, s69
	global_load_lds_dwordx4 v68, s[26:27]
	s_mov_b32 m0, s65
	v_mul_f32_e32 v62, 0xbfb8aa3b, v62
	v_mul_f32_e32 v63, 0xbfb8aa3b, v63
	global_load_lds_dwordx4 v0, s[60:61]
	s_mov_b32 m0, s66
	s_add_u32 s4, s13, s71
	v_exp_f32_e32 v62, v62
	v_exp_f32_e32 v63, v63
	global_load_lds_dwordx4 v66, s[60:61]
	s_addc_u32 s5, s62, 0
	s_mov_b32 m0, s67
	v_mov_b32_e32 v0, v188
	global_load_lds_dwordx4 v67, s[4:5]
	s_mov_b32 m0, s72
	v_pk_add_f32 v[62:63], v[62:63], 1.0 op_sel_hi:[1,0]
	global_load_lds_dwordx4 v68, s[4:5]
	v_mul_f32_e32 v58, 0xbfb8aa3b, v58
	v_ashrrev_i32_e32 v66, 2, v0
	v_and_b32_e32 v66, 0xffffffc0, v66
	v_and_or_b32 v67, v0, 15, s6
	v_add_u32_e32 v66, v67, v66
	v_rcp_f32_e32 v63, v63
	v_mul_f32_e32 v59, 0xbfb8aa3b, v59
	v_exp_f32_e32 v58, v58
	v_exp_f32_e32 v59, v59
	s_nop 0
	v_rcp_f32_e32 v62, v62
	v_pk_add_f32 v[58:59], v[58:59], 1.0 op_sel_hi:[1,0]
	v_lshrrev_b32_e32 v0, 1, v0
	v_and_b32_e32 v0, 0x78, v0
	v_cvt_pk_bf16_f32 v62, v62, v63
	v_mul_f32_e32 v63, 0xbfb8aa3b, v64
	v_exp_f32_e32 v64, v63
	v_mul_f32_e32 v63, 0xbfb8aa3b, v65
	v_exp_f32_e32 v65, v63
	v_or_b32_e32 v0, s36, v0
	v_readlane_b32 s37, v253, 32
	v_readlane_b32 s36, v254, 2
	v_pk_add_f32 v[64:65], v[64:65], 1.0 op_sel_hi:[1,0]
	v_readlane_b32 s37, v254, 3
	v_rcp_f32_e32 v63, v65
	v_mov_b32_e32 v76, v188
	v_rcp_f32_e32 v64, v64
	s_nop 0
	v_cvt_pk_bf16_f32 v63, v64, v63
	v_rcp_f32_e32 v59, v59
	v_rcp_f32_e32 v58, v58
	s_nop 0
	v_cvt_pk_bf16_f32 v64, v58, v59
	v_mul_f32_e32 v58, 0xbfb8aa3b, v60
	v_mul_f32_e32 v59, 0xbfb8aa3b, v61
	v_exp_f32_e32 v58, v58
	v_exp_f32_e32 v59, v59
	s_nop 0
	v_pk_add_f32 v[58:59], v[58:59], 1.0 op_sel_hi:[1,0]
	s_nop 0
	v_rcp_f32_e32 v59, v59
	v_rcp_f32_e32 v58, v58
	s_nop 0
	v_lshlrev_b64 v[60:61], 1, v[0:1]
	v_mul_f32_e32 v0, 0xbfb8aa3b, v54
	v_exp_f32_e32 v54, v0
	v_mul_f32_e32 v0, 0xbfb8aa3b, v55
	v_exp_f32_e32 v55, v0
	v_ashrrev_i32_e32 v67, 31, v66
	v_cvt_pk_bf16_f32 v65, v58, v59
	v_lshlrev_b64 v[58:59], 12, v[66:67]
	v_lshl_add_u64 v[58:59], s[36:37], 0, v[58:59]
	v_pk_add_f32 v[54:55], v[54:55], 1.0 op_sel_hi:[1,0]
	v_lshl_add_u64 v[58:59], v[58:59], 0, v[60:61]
	s_nop 4
	global_store_dwordx4 v[58:59], v[62:65], off
	s_nop 1
	v_rcp_f32_e32 v0, v55
	v_or_b32_e32 v62, 16, v66
	v_rcp_f32_e32 v54, v54
	s_nop 0
	v_cvt_pk_bf16_f32 v54, v54, v0
; DI unsigned pack2(float a, float b) { f32x2_t v = {a, b}; bf16x2_t r = __builtin_convertvector(v, bf16x2_t); return __builtin_bit_cast(unsigned, r); }
; DI float sigmoidf_(float x) { return 1.f / (1.f + __expf(-x)); }
; DI bfu* wsb(const PX& p, size_t off) { return (bfu*)(p.ws + off); }
; template <int EPI, int HM>
; DI void epi256(const PX& p, int l, f32x4 (&acc)[2][2][4][2], int brow, int bcol, int aux, bool src_input) {
;     ...
;           } else if (EPI == EPI_GATE) {
;             uint4 o;
;             o.x = pack2(sigmoidf_(v[0]), sigmoidf_(v[1])); o.y = pack2(sigmoidf_(v[2]), sigmoidf_(v[3]));
;             o.z = pack2(sigmoidf_(v[4]), sigmoidf_(v[5])); o.w = pack2(sigmoidf_(v[6]), sigmoidf_(v[7]));
;             *(uint4*)(wsb(p, OFF_BIG + B_ZML) + (size_t)row * 2048 + col0) = o;
	v_mul_f32_e32 v0, 0xbfb8aa3b, v56
	v_exp_f32_e32 v56, v0
	v_mul_f32_e32 v0, 0xbfb8aa3b, v57
	v_exp_f32_e32 v57, v0
	s_nop 0
	v_pk_add_f32 v[56:57], v[56:57], 1.0 op_sel_hi:[1,0]
	s_nop 0
	v_rcp_f32_e32 v0, v57
	v_rcp_f32_e32 v55, v56
	s_nop 0
	v_cvt_pk_bf16_f32 v55, v55, v0
	v_mul_f32_e32 v0, 0xbfb8aa3b, v50
	v_exp_f32_e32 v50, v0
	v_mul_f32_e32 v0, 0xbfb8aa3b, v51
	v_exp_f32_e32 v51, v0
	s_nop 0
	v_pk_add_f32 v[50:51], v[50:51], 1.0 op_sel_hi:[1,0]
	s_nop 0
	v_rcp_f32_e32 v0, v51
	v_rcp_f32_e32 v50, v50
	s_nop 0
	v_cvt_pk_bf16_f32 v56, v50, v0
	v_mul_f32_e32 v0, 0xbfb8aa3b, v52
	v_exp_f32_e32 v50, v0
	v_mul_f32_e32 v0, 0xbfb8aa3b, v53
	v_exp_f32_e32 v51, v0
	s_nop 0
	v_pk_add_f32 v[50:51], v[50:51], 1.0 op_sel_hi:[1,0]
	s_nop 0
	v_rcp_f32_e32 v0, v51
	v_rcp_f32_e32 v50, v50
	s_nop 0
	v_cvt_pk_bf16_f32 v57, v50, v0
	v_mul_f32_e32 v0, 0xbfb8aa3b, v46
	v_exp_f32_e32 v46, v0
	v_mul_f32_e32 v0, 0xbfb8aa3b, v47
	v_exp_f32_e32 v47, v0
	v_ashrrev_i32_e32 v63, 31, v62
	v_lshlrev_b64 v[50:51], 12, v[62:63]
	v_lshl_add_u64 v[50:51], s[36:37], 0, v[50:51]
	v_pk_add_f32 v[46:47], v[46:47], 1.0 op_sel_hi:[1,0]
	v_lshl_add_u64 v[50:51], v[50:51], 0, v[60:61]
	v_rcp_f32_e32 v0, v47
	global_store_dwordx4 v[50:51], v[54:57], off
	v_or_b32_e32 v52, 32, v66
	s_nop 0
	v_rcp_f32_e32 v46, v46
	s_nop 0
	v_cvt_pk_bf16_f32 v46, v46, v0
	v_mul_f32_e32 v0, 0xbfb8aa3b, v48
	v_exp_f32_e32 v48, v0
	v_mul_f32_e32 v0, 0xbfb8aa3b, v49
	v_exp_f32_e32 v49, v0
	s_nop 0
	v_pk_add_f32 v[48:49], v[48:49], 1.0 op_sel_hi:[1,0]
	s_nop 0
	v_rcp_f32_e32 v0, v49
	v_rcp_f32_e32 v47, v48
	s_nop 0
	v_cvt_pk_bf16_f32 v47, v47, v0
	v_mul_f32_e32 v0, 0xbfb8aa3b, v42
	v_exp_f32_e32 v42, v0
	v_mul_f32_e32 v0, 0xbfb8aa3b, v43
	v_exp_f32_e32 v43, v0
	s_nop 0
	v_pk_add_f32 v[42:43], v[42:43], 1.0 op_sel_hi:[1,0]
	s_nop 0
	v_rcp_f32_e32 v0, v43
	v_rcp_f32_e32 v42, v42
	s_nop 0
	v_cvt_pk_bf16_f32 v48, v42, v0
	v_mul_f32_e32 v0, 0xbfb8aa3b, v44
	v_exp_f32_e32 v42, v0
	v_mul_f32_e32 v0, 0xbfb8aa3b, v45
	v_exp_f32_e32 v43, v0
	s_nop 0
	v_pk_add_f32 v[42:43], v[42:43], 1.0 op_sel_hi:[1,0]
	s_nop 0
	v_rcp_f32_e32 v0, v43
	v_rcp_f32_e32 v42, v42
	s_nop 0
	v_cvt_pk_bf16_f32 v49, v42, v0
	v_mul_f32_e32 v0, 0xbfb8aa3b, v38
	v_exp_f32_e32 v38, v0
	v_mul_f32_e32 v0, 0xbfb8aa3b, v39
	v_exp_f32_e32 v39, v0
	v_ashrrev_i32_e32 v53, 31, v52
	v_lshlrev_b64 v[42:43], 12, v[52:53]
	v_lshl_add_u64 v[42:43], s[36:37], 0, v[42:43]
	v_pk_add_f32 v[38:39], v[38:39], 1.0 op_sel_hi:[1,0]
	v_lshl_add_u64 v[42:43], v[42:43], 0, v[60:61]
	v_rcp_f32_e32 v0, v39
	global_store_dwordx4 v[42:43], v[46:49], off
	v_or_b32_e32 v44, 48, v66
	s_nop 0
	v_rcp_f32_e32 v38, v38
	s_nop 0
	v_cvt_pk_bf16_f32 v38, v38, v0
	v_mul_f32_e32 v0, 0xbfb8aa3b, v40
	v_exp_f32_e32 v40, v0
	v_mul_f32_e32 v0, 0xbfb8aa3b, v41
	v_exp_f32_e32 v41, v0
	s_nop 0
	v_pk_add_f32 v[40:41], v[40:41], 1.0 op_sel_hi:[1,0]
	s_nop 0
	v_rcp_f32_e32 v0, v41
	v_rcp_f32_e32 v39, v40
	s_nop 0
	v_cvt_pk_bf16_f32 v39, v39, v0
	v_mul_f32_e32 v0, 0xbfb8aa3b, v34
	v_exp_f32_e32 v34, v0
	v_mul_f32_e32 v0, 0xbfb8aa3b, v35
	v_exp_f32_e32 v35, v0
	s_nop 0
	v_pk_add_f32 v[34:35], v[34:35], 1.0 op_sel_hi:[1,0]
	s_nop 0
	v_rcp_f32_e32 v0, v35
	v_rcp_f32_e32 v34, v34
	s_nop 0
	v_cvt_pk_bf16_f32 v40, v34, v0
	v_mul_f32_e32 v0, 0xbfb8aa3b, v36
	v_exp_f32_e32 v34, v0
	v_mul_f32_e32 v0, 0xbfb8aa3b, v37
	v_exp_f32_e32 v35, v0
	s_nop 0
	v_pk_add_f32 v[34:35], v[34:35], 1.0 op_sel_hi:[1,0]
	s_nop 0
	v_rcp_f32_e32 v0, v35
	v_rcp_f32_e32 v34, v34
	s_nop 0
	v_cvt_pk_bf16_f32 v41, v34, v0
	v_mul_f32_e32 v0, 0xbfb8aa3b, v30
	v_exp_f32_e32 v30, v0
	v_mul_f32_e32 v0, 0xbfb8aa3b, v31
	v_exp_f32_e32 v31, v0
	v_ashrrev_i32_e32 v45, 31, v44
	v_lshlrev_b64 v[34:35], 12, v[44:45]
	v_lshl_add_u64 v[34:35], s[36:37], 0, v[34:35]
	v_pk_add_f32 v[30:31], v[30:31], 1.0 op_sel_hi:[1,0]
	v_lshl_add_u64 v[34:35], v[34:35], 0, v[60:61]
	v_rcp_f32_e32 v0, v31
	global_store_dwordx4 v[34:35], v[38:41], off
	v_rcp_f32_e32 v30, v30
	s_nop 0
	v_cvt_pk_bf16_f32 v30, v30, v0
	v_mul_f32_e32 v0, 0xbfb8aa3b, v32
	v_exp_f32_e32 v32, v0
	v_mul_f32_e32 v0, 0xbfb8aa3b, v33
	v_exp_f32_e32 v33, v0
	s_nop 0
	v_pk_add_f32 v[32:33], v[32:33], 1.0 op_sel_hi:[1,0]
	s_nop 0
	v_rcp_f32_e32 v0, v33
	v_rcp_f32_e32 v31, v32
; DI unsigned pack2(float a, float b) { f32x2_t v = {a, b}; bf16x2_t r = __builtin_convertvector(v, bf16x2_t); return __builtin_bit_cast(unsigned, r); }
; DI float sigmoidf_(float x) { return 1.f / (1.f + __expf(-x)); }
; DI bfu* wsb(const PX& p, size_t off) { return (bfu*)(p.ws + off); }
; #define BAR __builtin_amdgcn_s_barrier()
; template <int HM>
; DI void kloop256(const PX& p, f32x4 (&acc)[2][2][4][2], const bfu* __restrict__ A, const bfu* __restrict__ Bt, const int K,
;                  const int brow, const int bcol, bfu* shm, const bool pre = false) {
;     ...
;   if (wr == 1) BAR;
; template <int EPI, int HM>
; DI void epi256(const PX& p, int l, f32x4 (&acc)[2][2][4][2], int brow, int bcol, int aux, bool src_input) {
;     ...
;           } else if (EPI == EPI_GATE) {
;             uint4 o;
;             o.x = pack2(sigmoidf_(v[0]), sigmoidf_(v[1])); o.y = pack2(sigmoidf_(v[2]), sigmoidf_(v[3]));
;             o.z = pack2(sigmoidf_(v[4]), sigmoidf_(v[5])); o.w = pack2(sigmoidf_(v[6]), sigmoidf_(v[7]));
;             *(uint4*)(wsb(p, OFF_BIG + B_ZML) + (size_t)row * 2048 + col0) = o;
	s_nop 0
	v_cvt_pk_bf16_f32 v31, v31, v0
	v_mul_f32_e32 v0, 0xbfb8aa3b, v26
	v_exp_f32_e32 v26, v0
	v_mul_f32_e32 v0, 0xbfb8aa3b, v27
	v_exp_f32_e32 v27, v0
	s_nop 0
	v_pk_add_f32 v[26:27], v[26:27], 1.0 op_sel_hi:[1,0]
	s_nop 0
	v_rcp_f32_e32 v0, v27
	v_rcp_f32_e32 v26, v26
	s_nop 0
	v_cvt_pk_bf16_f32 v32, v26, v0
	v_mul_f32_e32 v0, 0xbfb8aa3b, v28
	v_exp_f32_e32 v26, v0
	v_mul_f32_e32 v0, 0xbfb8aa3b, v29
	v_exp_f32_e32 v27, v0
	s_nop 0
	v_pk_add_f32 v[26:27], v[26:27], 1.0 op_sel_hi:[1,0]
	s_nop 0
	v_rcp_f32_e32 v0, v27
	v_rcp_f32_e32 v26, v26
	s_nop 0
	v_cvt_pk_bf16_f32 v33, v26, v0
	v_mul_f32_e32 v0, 0xbfb8aa3b, v22
	v_exp_f32_e32 v22, v0
	v_mul_f32_e32 v0, 0xbfb8aa3b, v23
	v_exp_f32_e32 v23, v0
	global_store_dwordx4 v[58:59], v[30:33], off offset:256
	v_pk_add_f32 v[22:23], v[22:23], 1.0 op_sel_hi:[1,0]
	s_nop 0
	v_rcp_f32_e32 v0, v23
	v_rcp_f32_e32 v22, v22
	s_nop 0
	v_cvt_pk_bf16_f32 v22, v22, v0
	v_mul_f32_e32 v0, 0xbfb8aa3b, v24
	v_exp_f32_e32 v24, v0
	v_mul_f32_e32 v0, 0xbfb8aa3b, v25
	v_exp_f32_e32 v25, v0
	s_nop 0
	v_pk_add_f32 v[24:25], v[24:25], 1.0 op_sel_hi:[1,0]
	s_nop 0
	v_rcp_f32_e32 v0, v25
	v_rcp_f32_e32 v23, v24
	s_nop 0
	v_cvt_pk_bf16_f32 v23, v23, v0
	v_mul_f32_e32 v0, 0xbfb8aa3b, v18
	v_exp_f32_e32 v18, v0
	v_mul_f32_e32 v0, 0xbfb8aa3b, v19
	v_exp_f32_e32 v19, v0
	s_nop 0
	v_pk_add_f32 v[18:19], v[18:19], 1.0 op_sel_hi:[1,0]
	s_nop 0
	v_rcp_f32_e32 v0, v19
	v_rcp_f32_e32 v18, v18
	s_nop 0
	v_cvt_pk_bf16_f32 v24, v18, v0
	v_mul_f32_e32 v0, 0xbfb8aa3b, v20
	v_exp_f32_e32 v18, v0
	v_mul_f32_e32 v0, 0xbfb8aa3b, v21
	v_exp_f32_e32 v19, v0
	s_nop 0
	v_pk_add_f32 v[18:19], v[18:19], 1.0 op_sel_hi:[1,0]
	s_nop 0
	v_rcp_f32_e32 v0, v19
	v_rcp_f32_e32 v18, v18
	s_nop 0
	v_cvt_pk_bf16_f32 v25, v18, v0
	v_mul_f32_e32 v0, 0xbfb8aa3b, v14
	v_exp_f32_e32 v14, v0
	v_mul_f32_e32 v0, 0xbfb8aa3b, v15
	v_exp_f32_e32 v15, v0
	global_store_dwordx4 v[50:51], v[22:25], off offset:256
	v_pk_add_f32 v[14:15], v[14:15], 1.0 op_sel_hi:[1,0]
	s_nop 0
	v_rcp_f32_e32 v0, v15
	v_rcp_f32_e32 v14, v14
	s_nop 0
	v_cvt_pk_bf16_f32 v14, v14, v0
	v_mul_f32_e32 v0, 0xbfb8aa3b, v16
	v_exp_f32_e32 v16, v0
	v_mul_f32_e32 v0, 0xbfb8aa3b, v17
	v_exp_f32_e32 v17, v0
	s_nop 0
	v_pk_add_f32 v[16:17], v[16:17], 1.0 op_sel_hi:[1,0]
	s_nop 0
	v_rcp_f32_e32 v0, v17
	v_rcp_f32_e32 v15, v16
	s_nop 0
	v_cvt_pk_bf16_f32 v15, v15, v0
	v_mul_f32_e32 v0, 0xbfb8aa3b, v10
	v_exp_f32_e32 v10, v0
	v_mul_f32_e32 v0, 0xbfb8aa3b, v11
	v_exp_f32_e32 v11, v0
	s_nop 0
	v_pk_add_f32 v[10:11], v[10:11], 1.0 op_sel_hi:[1,0]
	s_nop 0
	v_rcp_f32_e32 v0, v11
	v_rcp_f32_e32 v10, v10
	s_nop 0
	v_cvt_pk_bf16_f32 v16, v10, v0
	v_mul_f32_e32 v0, 0xbfb8aa3b, v12
	v_exp_f32_e32 v10, v0
	v_mul_f32_e32 v0, 0xbfb8aa3b, v13
	v_exp_f32_e32 v11, v0
	s_nop 0
	v_pk_add_f32 v[10:11], v[10:11], 1.0 op_sel_hi:[1,0]
	s_nop 0
	v_rcp_f32_e32 v0, v11
	v_rcp_f32_e32 v10, v10
	s_nop 0
	v_cvt_pk_bf16_f32 v17, v10, v0
	v_mul_f32_e32 v0, 0xbfb8aa3b, v6
	v_exp_f32_e32 v6, v0
	v_mul_f32_e32 v0, 0xbfb8aa3b, v7
	v_exp_f32_e32 v7, v0
	global_store_dwordx4 v[42:43], v[14:17], off offset:256
	v_pk_add_f32 v[6:7], v[6:7], 1.0 op_sel_hi:[1,0]
	s_nop 0
	v_rcp_f32_e32 v0, v7
	v_rcp_f32_e32 v6, v6
	s_nop 0
	v_cvt_pk_bf16_f32 v6, v6, v0
	v_mul_f32_e32 v0, 0xbfb8aa3b, v8
	v_exp_f32_e32 v8, v0
	v_mul_f32_e32 v0, 0xbfb8aa3b, v9
	v_exp_f32_e32 v9, v0
	s_nop 0
	v_pk_add_f32 v[8:9], v[8:9], 1.0 op_sel_hi:[1,0]
	s_nop 0
	v_rcp_f32_e32 v0, v9
	v_rcp_f32_e32 v7, v8
	s_nop 0
	v_cvt_pk_bf16_f32 v7, v7, v0
	v_mul_f32_e32 v0, 0xbfb8aa3b, v2
	v_exp_f32_e32 v2, v0
	v_mul_f32_e32 v0, 0xbfb8aa3b, v3
	v_exp_f32_e32 v3, v0
	s_nop 0
	v_pk_add_f32 v[2:3], v[2:3], 1.0 op_sel_hi:[1,0]
	s_nop 0
	v_rcp_f32_e32 v0, v3
	v_rcp_f32_e32 v2, v2
	s_nop 0
	v_cvt_pk_bf16_f32 v8, v2, v0
	v_mul_f32_e32 v0, 0xbfb8aa3b, v4
	v_exp_f32_e32 v2, v0
	v_mul_f32_e32 v0, 0xbfb8aa3b, v5
	v_exp_f32_e32 v3, v0
	s_nop 0
	v_pk_add_f32 v[2:3], v[2:3], 1.0 op_sel_hi:[1,0]
	s_nop 0
	v_rcp_f32_e32 v0, v3
	v_rcp_f32_e32 v2, v2
	s_nop 0
	v_cvt_pk_bf16_f32 v9, v2, v0
	global_store_dwordx4 v[34:35], v[6:9], off offset:256
	s_nop 0
	v_ashrrev_i32_e32 v0, 8, v76
	v_cmp_eq_u32_e32 vcc, 1, v0
	s_and_saveexec_b64 s[62:63], vcc
	s_cbranch_execz .LBB0_269
	s_barrier

; DI unsigned pack2(float a, float b) { f32x2_t v = {a, b}; bf16x2_t r = __builtin_convertvector(v, bf16x2_t); return __builtin_bit_cast(unsigned, r); }
; DI float sigmoidf_(float x) { return 1.f / (1.f + __expf(-x)); }
; DI bfu* wsb(const PX& p, size_t off) { return (bfu*)(p.ws + off); }
; DI void kstage4(const PX& p, const bfu* __restrict__ A, const bfu* __restrict__ Bt, const int K, const int brow, const int bcol, bfu* shm) {
;     ...
;   unsigned oa0, oa1, obb0, obb1;
;   { int r_, c_;
;     stage_rc(tid * 16, r_, c_); oa0 = (unsigned)(r_ * K + c_) * 2u;
;     { const int rho = r_ & 31, pr = (r_ & ~31) + 8 * ((rho & 15) >> 2) + 4 * (rho >> 4) + (rho & 3); obb0 = (unsigned)(pr * K + c_) * 2u; }
;     stage_rc(tid * 16 + 8192, r_, c_); oa1 = (unsigned)(r_ * K + c_) * 2u;
;     { const int rho = r_ & 31, pr = (r_ & ~31) + 8 * ((rho & 15) >> 2) + 4 * (rho >> 4) + (rho & 3); obb1 = (unsigned)(pr * K + c_) * 2u; } }
;     ...
;   KS_(shm + 4 * HT, Bt, bcol, obb0, obb1);
;   KS_(shm + 0 * HT, A, brow, oa0, oa1);
;   KS_(shm + 5 * HT, Bt, bcol + HALF, obb0, obb1);
;   KS_(shm + 1 * HT, A, brow + HALF, oa0, oa1);
; template <int EPI, int HM>
; DI void epi256(const PX& p, int l, f32x4 (&acc)[2][2][4][2], int brow, int bcol, int aux, bool src_input) {
;     ...
;           } else if (EPI == EPI_GATE) {
;             uint4 o;
;             o.x = pack2(sigmoidf_(v[0]), sigmoidf_(v[1])); o.y = pack2(sigmoidf_(v[2]), sigmoidf_(v[3]));
;             o.z = pack2(sigmoidf_(v[4]), sigmoidf_(v[5])); o.w = pack2(sigmoidf_(v[6]), sigmoidf_(v[7]));
;             *(uint4*)(wsb(p, OFF_BIG + B_ZML) + (size_t)row * 2048 + col0) = o;
.LBB0_307:
	s_or_b64 exec, exec, s[62:63]
	v_mov_b32_e32 v0, v188
	s_movk_i32 s36, 0x300
	v_ashrrev_i32_e32 v131, 31, v0
	v_lshrrev_b32_e32 v131, 26, v131
	v_lshlrev_b32_e32 v130, 4, v0
	v_add_u32_e32 v131, v0, v131
	v_bfe_i32 v0, v0, 27, 1
	v_lshrrev_b32_e32 v0, 22, v0
	v_add_u32_e32 v0, v130, v0
	v_and_b32_e32 v0, 0xfffffc00, v0
	v_sub_u32_e32 v0, v130, v0
	v_lshrrev_b32_e32 v132, 4, v0
	v_bitop3_b32 v0, v132, v0, 32 bitop3:0x6c
	v_ashrrev_i32_e32 v133, 31, v0
	v_ashrrev_i32_e32 v131, 6, v131
	v_lshrrev_b32_e32 v133, 26, v133
	v_lshlrev_b32_e32 v132, 3, v131
	v_add_u32_e32 v133, v0, v133
	v_and_b32_e32 v132, -16, v132
	v_ashrrev_i32_e32 v134, 6, v133
	v_and_b32_e32 v133, 0xc0, v133
	v_add_u32_e32 v132, v134, v132
	v_lshlrev_b32_e32 v131, 5, v131
	v_sub_u32_e32 v0, v0, v133
	v_and_b32_e32 v131, 32, v131
	v_ashrrev_i16_sdwa v0, v210, sext(v0) dst_sel:DWORD dst_unused:UNUSED_PAD src0_sel:DWORD src1_sel:BYTE_0
	v_lshlrev_b32_e32 v133, 1, v132
	v_lshrrev_b32_e32 v135, 2, v132
	v_and_b32_e32 v134, 3, v134
	s_mov_b32 s37, 0xffffe0
	v_add_u32_sdwa v0, v131, sext(v0) dst_sel:DWORD dst_unused:UNUSED_PAD src0_sel:DWORD src1_sel:WORD_0
	v_mul_lo_u32 v131, v132, s36
	v_and_b32_e32 v133, 24, v133
	v_and_b32_e32 v135, 4, v135
	v_and_or_b32 v132, v132, s37, v134
	v_or3_b32 v132, v132, v133, v135
	v_mul_u32_u24_e32 v132, 0x300, v132
	v_add_u32_e32 v130, 0x2000, v130
	v_add_lshl_u32 v131, v0, v131, 1
	v_add_lshl_u32 v0, v132, v0, 1
	v_ashrrev_i32_e32 v132, 31, v130
	v_lshrrev_b32_e32 v132, 22, v132
	v_add_u32_e32 v132, v130, v132
	v_ashrrev_i32_e32 v132, 10, v132
	s_cmp_eq_u32 s70, 1
	s_mov_b32 s0, 0x2f618100
	v_mul_i32_i24_e32 v133, 0x400, v132
	s_cselect_b32 s6, s0, 0x39818100
	s_mov_b32 s0, 0x1d88000
	v_sub_u32_e32 v130, v130, v133
	s_cselect_b32 s62, s0, 0x1f08000
	s_and_b64 s[0:1], s[4:5], exec
	v_lshrrev_b32_e32 v133, 4, v130
	s_cselect_b32 s1, 0x2c018100, s6
	v_bitop3_b32 v130, v133, v130, 32 bitop3:0x6c
	s_add_u32 s0, s96, s1
	v_ashrrev_i32_e32 v134, 31, v130
	s_addc_u32 s76, s97, 0
	v_lshrrev_b32_e32 v134, 26, v134
	s_and_b64 s[4:5], s[4:5], exec
	v_lshlrev_b32_e32 v133, 3, v132
	v_add_u32_e32 v134, v130, v134
	s_cselect_b32 s4, 0x1c08000, s62
	v_and_b32_e32 v133, -16, v133
	v_ashrrev_i32_e32 v135, 6, v134
	v_and_b32_e32 v134, 0xc0, v134
	s_lshl_b32 s6, s4, 1
	v_add_u32_e32 v133, v135, v133
	v_lshlrev_b32_e32 v132, 5, v132
	v_sub_u32_e32 v130, v130, v134
	s_add_u32 s4, s96, s6
	v_and_b32_e32 v132, 32, v132
	v_ashrrev_i16_sdwa v130, v210, sext(v130) dst_sel:DWORD dst_unused:UNUSED_PAD src0_sel:DWORD src1_sel:BYTE_0
	v_lshlrev_b32_e32 v134, 1, v133
	v_lshrrev_b32_e32 v136, 2, v133
	v_and_b32_e32 v135, 3, v135
	s_addc_u32 s5, s97, 0
	v_add_u32_sdwa v130, v132, sext(v130) dst_sel:DWORD dst_unused:UNUSED_PAD src0_sel:DWORD src1_sel:WORD_0
	v_mul_lo_u32 v132, v133, s36
	v_and_b32_e32 v134, 24, v134
	v_and_b32_e32 v136, 4, v136
	v_and_or_b32 v133, v133, s37, v135
	v_or3_b32 v133, v133, v134, v136
	s_add_u32 s62, s4, s9
	v_mul_u32_u24_e32 v133, 0x300, v133
	s_addc_u32 s63, s5, s43
	s_mov_b32 m0, s33
	v_add_lshl_u32 v132, v130, v132, 1
	v_add_lshl_u32 v130, v133, v130, 1
	global_load_lds_dwordx4 v0, s[62:63]
	s_mov_b32 m0, s64
	s_add_u32 s68, s0, s45
	global_load_lds_dwordx4 v130, s[62:63]
	s_mov_b32 s39, s69
	s_addc_u32 s69, s76, s69
	s_mov_b32 m0, s82
	s_add_u32 s74, s4, s17
	global_load_lds_dwordx4 v131, s[68:69]
	s_mov_b32 m0, s3
	s_addc_u32 s75, s5, s16
	global_load_lds_dwordx4 v132, s[68:69]
	s_mov_b32 m0, s65
	s_add_u32 s4, s0, s13
	global_load_lds_dwordx4 v0, s[74:75]
	s_mov_b32 m0, s66
	s_addc_u32 s5, s76, s12
	global_load_lds_dwordx4 v130, s[74:75]
	s_mov_b32 m0, s67
	v_mov_b32_e32 v0, v188
	global_load_lds_dwordx4 v131, s[4:5]
	s_mov_b32 m0, s72
	v_readlane_b32 s36, v254, 2
	global_load_lds_dwordx4 v132, s[4:5]
	v_readlane_b32 s37, v254, 3
	v_ashrrev_i32_e32 v130, 2, v0
	v_and_or_b32 v131, v0, 15, s8
	v_lshrrev_b32_e32 v0, 1, v0
	v_and_b32_e32 v0, 0x78, v0
	v_or_b32_e32 v132, s10, v0
	v_mul_f32_e32 v0, 0xbfb8aa3b, v126
	v_exp_f32_e32 v126, v0
	v_mul_f32_e32 v0, 0xbfb8aa3b, v127
	v_exp_f32_e32 v127, v0
	v_and_b32_e32 v130, 0xffffffc0, v130
	v_add_u32_e32 v130, v131, v130
	v_ashrrev_i32_e32 v133, 31, v132
	v_pk_add_f32 v[126:127], v[126:127], 1.0 op_sel_hi:[1,0]
	v_mov_b32_e32 v144, v188
	v_rcp_f32_e32 v0, v127
	s_mov_b32 s44, s45
	v_rcp_f32_e32 v126, v126
	s_nop 0
	v_cvt_pk_bf16_f32 v126, v126, v0
	v_mul_f32_e32 v0, 0xbfb8aa3b, v128
	v_exp_f32_e32 v128, v0
	v_mul_f32_e32 v0, 0xbfb8aa3b, v129
	v_exp_f32_e32 v129, v0
	s_nop 0
	v_pk_add_f32 v[128:129], v[128:129], 1.0 op_sel_hi:[1,0]
	s_nop 0
	v_rcp_f32_e32 v0, v129
	v_rcp_f32_e32 v127, v128
	s_nop 0
	v_cvt_pk_bf16_f32 v127, v127, v0
	v_mul_f32_e32 v0, 0xbfb8aa3b, v122
	v_exp_f32_e32 v122, v0
	v_mul_f32_e32 v0, 0xbfb8aa3b, v123
	v_exp_f32_e32 v123, v0
	s_nop 0
	v_pk_add_f32 v[122:123], v[122:123], 1.0 op_sel_hi:[1,0]
	s_nop 0
	v_rcp_f32_e32 v0, v123
	v_rcp_f32_e32 v122, v122
	s_nop 0
	v_cvt_pk_bf16_f32 v128, v122, v0
	v_mul_f32_e32 v0, 0xbfb8aa3b, v124
	v_exp_f32_e32 v122, v0
	v_mul_f32_e32 v0, 0xbfb8aa3b, v125
	v_exp_f32_e32 v123, v0
	s_nop 0
	v_pk_add_f32 v[122:123], v[122:123], 1.0 op_sel_hi:[1,0]
	s_nop 0
	v_rcp_f32_e32 v0, v123
	v_rcp_f32_e32 v122, v122
	s_nop 0
	v_cvt_pk_bf16_f32 v129, v122, v0
	v_mul_f32_e32 v0, 0xbfb8aa3b, v118
	v_exp_f32_e32 v118, v0
	v_mul_f32_e32 v0, 0xbfb8aa3b, v119
	v_exp_f32_e32 v119, v0
	v_ashrrev_i32_e32 v131, 31, v130
	v_lshlrev_b64 v[122:123], 12, v[130:131]
	v_lshl_add_u64 v[124:125], s[36:37], 0, v[122:123]
	v_lshlrev_b64 v[122:123], 1, v[132:133]
	v_pk_add_f32 v[118:119], v[118:119], 1.0 op_sel_hi:[1,0]
	v_lshl_add_u64 v[124:125], v[124:125], 0, v[122:123]
; DI unsigned pack2(float a, float b) { f32x2_t v = {a, b}; bf16x2_t r = __builtin_convertvector(v, bf16x2_t); return __builtin_bit_cast(unsigned, r); }
; DI float sigmoidf_(float x) { return 1.f / (1.f + __expf(-x)); }
; DI bfu* wsb(const PX& p, size_t off) { return (bfu*)(p.ws + off); }
; template <int EPI, int HM>
; DI void epi256(const PX& p, int l, f32x4 (&acc)[2][2][4][2], int brow, int bcol, int aux, bool src_input) {
;     ...
;           } else if (EPI == EPI_GATE) {
;             uint4 o;
;             o.x = pack2(sigmoidf_(v[0]), sigmoidf_(v[1])); o.y = pack2(sigmoidf_(v[2]), sigmoidf_(v[3]));
;             o.z = pack2(sigmoidf_(v[4]), sigmoidf_(v[5])); o.w = pack2(sigmoidf_(v[6]), sigmoidf_(v[7]));
;             *(uint4*)(wsb(p, OFF_BIG + B_ZML) + (size_t)row * 2048 + col0) = o;
	s_nop 4
	global_store_dwordx4 v[124:125], v[126:129], off
	s_nop 1
	v_rcp_f32_e32 v0, v119
	v_or_b32_e32 v126, 16, v130
	v_rcp_f32_e32 v118, v118
	s_nop 0
	v_cvt_pk_bf16_f32 v118, v118, v0
	v_mul_f32_e32 v0, 0xbfb8aa3b, v120
	v_exp_f32_e32 v120, v0
	v_mul_f32_e32 v0, 0xbfb8aa3b, v121
	v_exp_f32_e32 v121, v0
	s_nop 0
	v_pk_add_f32 v[120:121], v[120:121], 1.0 op_sel_hi:[1,0]
	s_nop 0
	v_rcp_f32_e32 v0, v121
	v_rcp_f32_e32 v119, v120
	s_nop 0
	v_cvt_pk_bf16_f32 v119, v119, v0
	v_mul_f32_e32 v0, 0xbfb8aa3b, v114
	v_exp_f32_e32 v114, v0
	v_mul_f32_e32 v0, 0xbfb8aa3b, v115
	v_exp_f32_e32 v115, v0
	s_nop 0
	v_pk_add_f32 v[114:115], v[114:115], 1.0 op_sel_hi:[1,0]
	s_nop 0
	v_rcp_f32_e32 v0, v115
	v_rcp_f32_e32 v114, v114
	s_nop 0
	v_cvt_pk_bf16_f32 v120, v114, v0
	v_mul_f32_e32 v0, 0xbfb8aa3b, v116
	v_exp_f32_e32 v114, v0
	v_mul_f32_e32 v0, 0xbfb8aa3b, v117
	v_exp_f32_e32 v115, v0
	s_nop 0
	v_pk_add_f32 v[114:115], v[114:115], 1.0 op_sel_hi:[1,0]
	s_nop 0
	v_rcp_f32_e32 v0, v115
	v_rcp_f32_e32 v114, v114
	s_nop 0
	v_cvt_pk_bf16_f32 v121, v114, v0
	v_mul_f32_e32 v0, 0xbfb8aa3b, v110
	v_exp_f32_e32 v110, v0
	v_mul_f32_e32 v0, 0xbfb8aa3b, v111
	v_exp_f32_e32 v111, v0
	v_ashrrev_i32_e32 v127, 31, v126
	v_lshlrev_b64 v[114:115], 12, v[126:127]
	v_lshl_add_u64 v[114:115], s[36:37], 0, v[114:115]
	v_pk_add_f32 v[110:111], v[110:111], 1.0 op_sel_hi:[1,0]
	v_lshl_add_u64 v[114:115], v[114:115], 0, v[122:123]
	v_rcp_f32_e32 v0, v111
	global_store_dwordx4 v[114:115], v[118:121], off
	v_or_b32_e32 v116, 32, v130
	s_nop 0
	v_rcp_f32_e32 v110, v110
	s_nop 0
	v_cvt_pk_bf16_f32 v110, v110, v0
	v_mul_f32_e32 v0, 0xbfb8aa3b, v112
	v_exp_f32_e32 v112, v0
	v_mul_f32_e32 v0, 0xbfb8aa3b, v113
	v_exp_f32_e32 v113, v0
	s_nop 0
	v_pk_add_f32 v[112:113], v[112:113], 1.0 op_sel_hi:[1,0]
	s_nop 0
	v_rcp_f32_e32 v0, v113
	v_rcp_f32_e32 v111, v112
	s_nop 0
	v_cvt_pk_bf16_f32 v111, v111, v0
	v_mul_f32_e32 v0, 0xbfb8aa3b, v106
	v_exp_f32_e32 v106, v0
	v_mul_f32_e32 v0, 0xbfb8aa3b, v107
	v_exp_f32_e32 v107, v0
	s_nop 0
	v_pk_add_f32 v[106:107], v[106:107], 1.0 op_sel_hi:[1,0]
	s_nop 0
	v_rcp_f32_e32 v0, v107
	v_rcp_f32_e32 v106, v106
	s_nop 0
	v_cvt_pk_bf16_f32 v112, v106, v0
	v_mul_f32_e32 v0, 0xbfb8aa3b, v108
	v_exp_f32_e32 v106, v0
	v_mul_f32_e32 v0, 0xbfb8aa3b, v109
	v_exp_f32_e32 v107, v0
	s_nop 0
	v_pk_add_f32 v[106:107], v[106:107], 1.0 op_sel_hi:[1,0]
	s_nop 0
	v_rcp_f32_e32 v0, v107
	v_rcp_f32_e32 v106, v106
	s_nop 0
	v_cvt_pk_bf16_f32 v113, v106, v0
	v_mul_f32_e32 v0, 0xbfb8aa3b, v102
	v_exp_f32_e32 v102, v0
	v_mul_f32_e32 v0, 0xbfb8aa3b, v103
	v_exp_f32_e32 v103, v0
	v_ashrrev_i32_e32 v117, 31, v116
	v_lshlrev_b64 v[106:107], 12, v[116:117]
	v_lshl_add_u64 v[106:107], s[36:37], 0, v[106:107]
	v_pk_add_f32 v[102:103], v[102:103], 1.0 op_sel_hi:[1,0]
	v_lshl_add_u64 v[106:107], v[106:107], 0, v[122:123]
	v_rcp_f32_e32 v0, v103
	global_store_dwordx4 v[106:107], v[110:113], off
	v_or_b32_e32 v108, 48, v130
	s_nop 0
	v_rcp_f32_e32 v102, v102
	s_nop 0
	v_cvt_pk_bf16_f32 v102, v102, v0
	v_mul_f32_e32 v0, 0xbfb8aa3b, v104
	v_exp_f32_e32 v104, v0
	v_mul_f32_e32 v0, 0xbfb8aa3b, v105
	v_exp_f32_e32 v105, v0
	s_nop 0
	v_pk_add_f32 v[104:105], v[104:105], 1.0 op_sel_hi:[1,0]
	s_nop 0
	v_rcp_f32_e32 v0, v105
	v_rcp_f32_e32 v103, v104
	s_nop 0
	v_cvt_pk_bf16_f32 v103, v103, v0
	v_mul_f32_e32 v0, 0xbfb8aa3b, v98
	v_exp_f32_e32 v98, v0
	v_mul_f32_e32 v0, 0xbfb8aa3b, v99
	v_exp_f32_e32 v99, v0
	s_nop 0
	v_pk_add_f32 v[98:99], v[98:99], 1.0 op_sel_hi:[1,0]
	s_nop 0
	v_rcp_f32_e32 v0, v99
	v_rcp_f32_e32 v98, v98
	s_nop 0
	v_cvt_pk_bf16_f32 v104, v98, v0
	v_mul_f32_e32 v0, 0xbfb8aa3b, v100
	v_exp_f32_e32 v98, v0
	v_mul_f32_e32 v0, 0xbfb8aa3b, v101
	v_exp_f32_e32 v99, v0
	s_nop 0
	v_pk_add_f32 v[98:99], v[98:99], 1.0 op_sel_hi:[1,0]
	s_nop 0
	v_rcp_f32_e32 v0, v99
	v_rcp_f32_e32 v98, v98
	s_nop 0
	v_cvt_pk_bf16_f32 v105, v98, v0
	v_mul_f32_e32 v0, 0xbfb8aa3b, v94
	v_exp_f32_e32 v94, v0
	v_mul_f32_e32 v0, 0xbfb8aa3b, v95
	v_exp_f32_e32 v95, v0
	v_ashrrev_i32_e32 v109, 31, v108
	v_lshlrev_b64 v[98:99], 12, v[108:109]
	v_lshl_add_u64 v[98:99], s[36:37], 0, v[98:99]
	v_pk_add_f32 v[94:95], v[94:95], 1.0 op_sel_hi:[1,0]
	v_lshl_add_u64 v[98:99], v[98:99], 0, v[122:123]
	v_rcp_f32_e32 v0, v95
	global_store_dwordx4 v[98:99], v[102:105], off
	v_rcp_f32_e32 v94, v94
	s_nop 0
	v_cvt_pk_bf16_f32 v94, v94, v0
	v_mul_f32_e32 v0, 0xbfb8aa3b, v96
	v_exp_f32_e32 v96, v0
	v_mul_f32_e32 v0, 0xbfb8aa3b, v97
	v_exp_f32_e32 v97, v0
	s_nop 0
	v_pk_add_f32 v[96:97], v[96:97], 1.0 op_sel_hi:[1,0]
	s_nop 0
	v_rcp_f32_e32 v0, v97
	v_rcp_f32_e32 v95, v96
	s_nop 0
	v_cvt_pk_bf16_f32 v95, v95, v0
	v_mul_f32_e32 v0, 0xbfb8aa3b, v90
	v_exp_f32_e32 v90, v0
	v_mul_f32_e32 v0, 0xbfb8aa3b, v91
	v_exp_f32_e32 v91, v0
	s_nop 0
	v_pk_add_f32 v[90:91], v[90:91], 1.0 op_sel_hi:[1,0]
	s_nop 0
	v_rcp_f32_e32 v0, v91
	v_rcp_f32_e32 v90, v90
	s_nop 0
	v_cvt_pk_bf16_f32 v96, v90, v0
	v_mul_f32_e32 v0, 0xbfb8aa3b, v92
	v_exp_f32_e32 v90, v0
	v_mul_f32_e32 v0, 0xbfb8aa3b, v93
	v_exp_f32_e32 v91, v0
	s_nop 0
	v_pk_add_f32 v[90:91], v[90:91], 1.0 op_sel_hi:[1,0]
	s_nop 0
	v_rcp_f32_e32 v0, v91
	v_rcp_f32_e32 v90, v90
	s_nop 0
	v_cvt_pk_bf16_f32 v97, v90, v0
	v_mul_f32_e32 v0, 0xbfb8aa3b, v86
	v_exp_f32_e32 v86, v0
	v_mul_f32_e32 v0, 0xbfb8aa3b, v87
	v_exp_f32_e32 v87, v0
	global_store_dwordx4 v[124:125], v[94:97], off offset:256
	v_pk_add_f32 v[86:87], v[86:87], 1.0 op_sel_hi:[1,0]
	s_nop 0
	v_rcp_f32_e32 v0, v87
	v_rcp_f32_e32 v86, v86
	s_nop 0
	v_cvt_pk_bf16_f32 v86, v86, v0
	v_mul_f32_e32 v0, 0xbfb8aa3b, v88
	v_exp_f32_e32 v88, v0
	v_mul_f32_e32 v0, 0xbfb8aa3b, v89
	v_exp_f32_e32 v89, v0
	s_nop 0
	v_pk_add_f32 v[88:89], v[88:89], 1.0 op_sel_hi:[1,0]
; DI unsigned pack2(float a, float b) { f32x2_t v = {a, b}; bf16x2_t r = __builtin_convertvector(v, bf16x2_t); return __builtin_bit_cast(unsigned, r); }
; DI float sigmoidf_(float x) { return 1.f / (1.f + __expf(-x)); }
; DI bfu* wsb(const PX& p, size_t off) { return (bfu*)(p.ws + off); }
; template <int EPI, int HM>
; DI void epi256(const PX& p, int l, f32x4 (&acc)[2][2][4][2], int brow, int bcol, int aux, bool src_input) {
;     ...
;           } else if (EPI == EPI_GATE) {
;             uint4 o;
;             o.x = pack2(sigmoidf_(v[0]), sigmoidf_(v[1])); o.y = pack2(sigmoidf_(v[2]), sigmoidf_(v[3]));
;             o.z = pack2(sigmoidf_(v[4]), sigmoidf_(v[5])); o.w = pack2(sigmoidf_(v[6]), sigmoidf_(v[7]));
;             *(uint4*)(wsb(p, OFF_BIG + B_ZML) + (size_t)row * 2048 + col0) = o;
	s_nop 0
	v_rcp_f32_e32 v0, v89
	v_rcp_f32_e32 v87, v88
	s_nop 0
	v_cvt_pk_bf16_f32 v87, v87, v0
	v_mul_f32_e32 v0, 0xbfb8aa3b, v82
	v_exp_f32_e32 v82, v0
	v_mul_f32_e32 v0, 0xbfb8aa3b, v83
	v_exp_f32_e32 v83, v0
	s_nop 0
	v_pk_add_f32 v[82:83], v[82:83], 1.0 op_sel_hi:[1,0]
	s_nop 0
	v_rcp_f32_e32 v0, v83
	v_rcp_f32_e32 v82, v82
	s_nop 0
	v_cvt_pk_bf16_f32 v88, v82, v0
	v_mul_f32_e32 v0, 0xbfb8aa3b, v84
	v_exp_f32_e32 v82, v0
	v_mul_f32_e32 v0, 0xbfb8aa3b, v85
	v_exp_f32_e32 v83, v0
	s_nop 0
	v_pk_add_f32 v[82:83], v[82:83], 1.0 op_sel_hi:[1,0]
	s_nop 0
	v_rcp_f32_e32 v0, v83
	v_rcp_f32_e32 v82, v82
	s_nop 0
	v_cvt_pk_bf16_f32 v89, v82, v0
	v_mul_f32_e32 v0, 0xbfb8aa3b, v78
	v_exp_f32_e32 v78, v0
	v_mul_f32_e32 v0, 0xbfb8aa3b, v79
	v_exp_f32_e32 v79, v0
	global_store_dwordx4 v[114:115], v[86:89], off offset:256
	v_pk_add_f32 v[78:79], v[78:79], 1.0 op_sel_hi:[1,0]
	s_nop 0
	v_rcp_f32_e32 v0, v79
	v_rcp_f32_e32 v78, v78
	s_nop 0
	v_cvt_pk_bf16_f32 v78, v78, v0
	v_mul_f32_e32 v0, 0xbfb8aa3b, v80
	v_exp_f32_e32 v80, v0
	v_mul_f32_e32 v0, 0xbfb8aa3b, v81
	v_exp_f32_e32 v81, v0
	s_nop 0
	v_pk_add_f32 v[80:81], v[80:81], 1.0 op_sel_hi:[1,0]
	s_nop 0
	v_rcp_f32_e32 v0, v81
	v_rcp_f32_e32 v79, v80
	s_nop 0
	v_cvt_pk_bf16_f32 v79, v79, v0
	v_mul_f32_e32 v0, 0xbfb8aa3b, v74
	v_exp_f32_e32 v74, v0
	v_mul_f32_e32 v0, 0xbfb8aa3b, v75
	v_exp_f32_e32 v75, v0
	s_nop 0
	v_pk_add_f32 v[74:75], v[74:75], 1.0 op_sel_hi:[1,0]
	s_nop 0
	v_rcp_f32_e32 v0, v75
	v_rcp_f32_e32 v74, v74
	s_nop 0
	v_cvt_pk_bf16_f32 v80, v74, v0
	v_mul_f32_e32 v0, 0xbfb8aa3b, v76
	v_exp_f32_e32 v74, v0
	v_mul_f32_e32 v0, 0xbfb8aa3b, v77
	v_exp_f32_e32 v75, v0
	s_nop 0
	v_pk_add_f32 v[74:75], v[74:75], 1.0 op_sel_hi:[1,0]
	s_nop 0
	v_rcp_f32_e32 v0, v75
	v_rcp_f32_e32 v74, v74
	s_nop 0
	v_cvt_pk_bf16_f32 v81, v74, v0
	v_mul_f32_e32 v0, 0xbfb8aa3b, v70
	v_exp_f32_e32 v70, v0
	v_mul_f32_e32 v0, 0xbfb8aa3b, v71
	v_exp_f32_e32 v71, v0
	global_store_dwordx4 v[106:107], v[78:81], off offset:256
	v_pk_add_f32 v[70:71], v[70:71], 1.0 op_sel_hi:[1,0]
	s_nop 0
	v_rcp_f32_e32 v0, v71
	v_rcp_f32_e32 v70, v70
	s_nop 0
	v_cvt_pk_bf16_f32 v70, v70, v0
	v_mul_f32_e32 v0, 0xbfb8aa3b, v72
	v_exp_f32_e32 v72, v0
	v_mul_f32_e32 v0, 0xbfb8aa3b, v73
	v_exp_f32_e32 v73, v0
	s_nop 0
	v_pk_add_f32 v[72:73], v[72:73], 1.0 op_sel_hi:[1,0]
	s_nop 0
	v_rcp_f32_e32 v0, v73
	v_rcp_f32_e32 v71, v72
	s_nop 0
	v_cvt_pk_bf16_f32 v71, v71, v0
	v_mul_f32_e32 v0, 0xbfb8aa3b, v66
	v_exp_f32_e32 v66, v0
	v_mul_f32_e32 v0, 0xbfb8aa3b, v67
	v_exp_f32_e32 v67, v0
	s_nop 0
	v_pk_add_f32 v[66:67], v[66:67], 1.0 op_sel_hi:[1,0]
	s_nop 0
	v_rcp_f32_e32 v0, v67
	v_rcp_f32_e32 v66, v66
	s_nop 0
	v_cvt_pk_bf16_f32 v72, v66, v0
	v_mul_f32_e32 v0, 0xbfb8aa3b, v68
	v_exp_f32_e32 v66, v0
	v_mul_f32_e32 v0, 0xbfb8aa3b, v69
	v_exp_f32_e32 v67, v0
	s_nop 0
	v_pk_add_f32 v[66:67], v[66:67], 1.0 op_sel_hi:[1,0]
	s_nop 0
	v_rcp_f32_e32 v0, v67
	v_rcp_f32_e32 v66, v66
	s_nop 0
	v_cvt_pk_bf16_f32 v73, v66, v0
	v_mul_f32_e32 v0, 0xbfb8aa3b, v62
	v_exp_f32_e32 v62, v0
	v_mul_f32_e32 v0, 0xbfb8aa3b, v63
	v_exp_f32_e32 v63, v0
	global_store_dwordx4 v[98:99], v[70:73], off offset:256
	v_add_u32_e32 v66, 0x80, v130
	v_pk_add_f32 v[62:63], v[62:63], 1.0 op_sel_hi:[1,0]
	s_nop 0
	v_rcp_f32_e32 v0, v63
	v_rcp_f32_e32 v62, v62
	s_nop 0
	v_cvt_pk_bf16_f32 v62, v62, v0
	v_mul_f32_e32 v0, 0xbfb8aa3b, v64
	v_exp_f32_e32 v64, v0
	v_mul_f32_e32 v0, 0xbfb8aa3b, v65
	v_exp_f32_e32 v65, v0
	s_nop 0
	v_pk_add_f32 v[64:65], v[64:65], 1.0 op_sel_hi:[1,0]
	s_nop 0
	v_rcp_f32_e32 v0, v65
	v_rcp_f32_e32 v63, v64
	s_nop 0
	v_cvt_pk_bf16_f32 v63, v63, v0
	v_mul_f32_e32 v0, 0xbfb8aa3b, v58
	v_exp_f32_e32 v58, v0
	v_mul_f32_e32 v0, 0xbfb8aa3b, v59
	v_exp_f32_e32 v59, v0
	s_nop 0
	v_pk_add_f32 v[58:59], v[58:59], 1.0 op_sel_hi:[1,0]
	s_nop 0
	v_rcp_f32_e32 v0, v59
	v_rcp_f32_e32 v58, v58
	s_nop 0
	v_cvt_pk_bf16_f32 v64, v58, v0
	v_mul_f32_e32 v0, 0xbfb8aa3b, v60
	v_exp_f32_e32 v58, v0
	v_mul_f32_e32 v0, 0xbfb8aa3b, v61
	v_exp_f32_e32 v59, v0
	s_nop 0
	v_pk_add_f32 v[58:59], v[58:59], 1.0 op_sel_hi:[1,0]
	s_nop 0
	v_rcp_f32_e32 v0, v59
	v_rcp_f32_e32 v58, v58
	s_nop 0
	v_cvt_pk_bf16_f32 v65, v58, v0
	v_mul_f32_e32 v0, 0xbfb8aa3b, v54
	v_exp_f32_e32 v54, v0
	v_mul_f32_e32 v0, 0xbfb8aa3b, v55
	v_exp_f32_e32 v55, v0
	v_ashrrev_i32_e32 v67, 31, v66
	v_lshlrev_b64 v[58:59], 12, v[66:67]
	v_lshl_add_u64 v[58:59], s[36:37], 0, v[58:59]
	v_pk_add_f32 v[54:55], v[54:55], 1.0 op_sel_hi:[1,0]
	v_lshl_add_u64 v[58:59], v[58:59], 0, v[122:123]
	v_rcp_f32_e32 v0, v55
	global_store_dwordx4 v[58:59], v[62:65], off
	v_add_u32_e32 v60, 0x90, v130
	s_nop 0
	v_rcp_f32_e32 v54, v54
	s_nop 0
	v_cvt_pk_bf16_f32 v54, v54, v0
	v_mul_f32_e32 v0, 0xbfb8aa3b, v56
	v_exp_f32_e32 v56, v0
	v_mul_f32_e32 v0, 0xbfb8aa3b, v57
	v_exp_f32_e32 v57, v0
	s_nop 0
	v_pk_add_f32 v[56:57], v[56:57], 1.0 op_sel_hi:[1,0]
	s_nop 0
	v_rcp_f32_e32 v0, v57
	v_rcp_f32_e32 v55, v56
	s_nop 0
	v_cvt_pk_bf16_f32 v55, v55, v0
	v_mul_f32_e32 v0, 0xbfb8aa3b, v50
	v_exp_f32_e32 v50, v0
	v_mul_f32_e32 v0, 0xbfb8aa3b, v51
	v_exp_f32_e32 v51, v0
	s_nop 0
	v_pk_add_f32 v[50:51], v[50:51], 1.0 op_sel_hi:[1,0]
	s_nop 0
	v_rcp_f32_e32 v0, v51
	v_rcp_f32_e32 v50, v50
	s_nop 0
	v_cvt_pk_bf16_f32 v56, v50, v0
	v_mul_f32_e32 v0, 0xbfb8aa3b, v52
	v_exp_f32_e32 v50, v0
	v_mul_f32_e32 v0, 0xbfb8aa3b, v53
	v_exp_f32_e32 v51, v0
	s_nop 0
	v_pk_add_f32 v[50:51], v[50:51], 1.0 op_sel_hi:[1,0]
	s_nop 0
	v_rcp_f32_e32 v0, v51
	v_rcp_f32_e32 v50, v50
	s_nop 0
	v_cvt_pk_bf16_f32 v57, v50, v0
	v_mul_f32_e32 v0, 0xbfb8aa3b, v46
	v_exp_f32_e32 v46, v0
	v_mul_f32_e32 v0, 0xbfb8aa3b, v47
	v_exp_f32_e32 v47, v0
	v_ashrrev_i32_e32 v61, 31, v60
; DI unsigned pack2(float a, float b) { f32x2_t v = {a, b}; bf16x2_t r = __builtin_convertvector(v, bf16x2_t); return __builtin_bit_cast(unsigned, r); }
; DI float sigmoidf_(float x) { return 1.f / (1.f + __expf(-x)); }
; DI bfu* wsb(const PX& p, size_t off) { return (bfu*)(p.ws + off); }
; template <int EPI, int HM>
; DI void epi256(const PX& p, int l, f32x4 (&acc)[2][2][4][2], int brow, int bcol, int aux, bool src_input) {
;     ...
;           } else if (EPI == EPI_GATE) {
;             uint4 o;
;             o.x = pack2(sigmoidf_(v[0]), sigmoidf_(v[1])); o.y = pack2(sigmoidf_(v[2]), sigmoidf_(v[3]));
;             o.z = pack2(sigmoidf_(v[4]), sigmoidf_(v[5])); o.w = pack2(sigmoidf_(v[6]), sigmoidf_(v[7]));
;             *(uint4*)(wsb(p, OFF_BIG + B_ZML) + (size_t)row * 2048 + col0) = o;
	v_lshlrev_b64 v[50:51], 12, v[60:61]
	v_lshl_add_u64 v[50:51], s[36:37], 0, v[50:51]
	v_pk_add_f32 v[46:47], v[46:47], 1.0 op_sel_hi:[1,0]
	v_lshl_add_u64 v[50:51], v[50:51], 0, v[122:123]
	v_rcp_f32_e32 v0, v47
	global_store_dwordx4 v[50:51], v[54:57], off
	v_add_u32_e32 v52, 0xa0, v130
	s_nop 0
	v_rcp_f32_e32 v46, v46
	s_nop 0
	v_cvt_pk_bf16_f32 v46, v46, v0
	v_mul_f32_e32 v0, 0xbfb8aa3b, v48
	v_exp_f32_e32 v48, v0
	v_mul_f32_e32 v0, 0xbfb8aa3b, v49
	v_exp_f32_e32 v49, v0
	s_nop 0
	v_pk_add_f32 v[48:49], v[48:49], 1.0 op_sel_hi:[1,0]
	s_nop 0
	v_rcp_f32_e32 v0, v49
	v_rcp_f32_e32 v47, v48
	s_nop 0
	v_cvt_pk_bf16_f32 v47, v47, v0
	v_mul_f32_e32 v0, 0xbfb8aa3b, v42
	v_exp_f32_e32 v42, v0
	v_mul_f32_e32 v0, 0xbfb8aa3b, v43
	v_exp_f32_e32 v43, v0
	s_nop 0
	v_pk_add_f32 v[42:43], v[42:43], 1.0 op_sel_hi:[1,0]
	s_nop 0
	v_rcp_f32_e32 v0, v43
	v_rcp_f32_e32 v42, v42
	s_nop 0
	v_cvt_pk_bf16_f32 v48, v42, v0
	v_mul_f32_e32 v0, 0xbfb8aa3b, v44
	v_exp_f32_e32 v42, v0
	v_mul_f32_e32 v0, 0xbfb8aa3b, v45
	v_exp_f32_e32 v43, v0
	s_nop 0
	v_pk_add_f32 v[42:43], v[42:43], 1.0 op_sel_hi:[1,0]
	s_nop 0
	v_rcp_f32_e32 v0, v43
	v_rcp_f32_e32 v42, v42
	s_nop 0
	v_cvt_pk_bf16_f32 v49, v42, v0
	v_mul_f32_e32 v0, 0xbfb8aa3b, v38
	v_exp_f32_e32 v38, v0
	v_mul_f32_e32 v0, 0xbfb8aa3b, v39
	v_exp_f32_e32 v39, v0
	v_ashrrev_i32_e32 v53, 31, v52
	v_lshlrev_b64 v[42:43], 12, v[52:53]
	v_lshl_add_u64 v[42:43], s[36:37], 0, v[42:43]
	v_pk_add_f32 v[38:39], v[38:39], 1.0 op_sel_hi:[1,0]
	v_lshl_add_u64 v[42:43], v[42:43], 0, v[122:123]
	v_rcp_f32_e32 v0, v39
	global_store_dwordx4 v[42:43], v[46:49], off
	v_add_u32_e32 v44, 0xb0, v130
	s_nop 0
	v_rcp_f32_e32 v38, v38
	s_nop 0
	v_cvt_pk_bf16_f32 v38, v38, v0
	v_mul_f32_e32 v0, 0xbfb8aa3b, v40
	v_exp_f32_e32 v40, v0
	v_mul_f32_e32 v0, 0xbfb8aa3b, v41
	v_exp_f32_e32 v41, v0
	s_nop 0
	v_pk_add_f32 v[40:41], v[40:41], 1.0 op_sel_hi:[1,0]
	s_nop 0
	v_rcp_f32_e32 v0, v41
	v_rcp_f32_e32 v39, v40
	s_nop 0
	v_cvt_pk_bf16_f32 v39, v39, v0
	v_mul_f32_e32 v0, 0xbfb8aa3b, v34
	v_exp_f32_e32 v34, v0
	v_mul_f32_e32 v0, 0xbfb8aa3b, v35
	v_exp_f32_e32 v35, v0
	s_nop 0
	v_pk_add_f32 v[34:35], v[34:35], 1.0 op_sel_hi:[1,0]
	s_nop 0
	v_rcp_f32_e32 v0, v35
	v_rcp_f32_e32 v34, v34
	s_nop 0
	v_cvt_pk_bf16_f32 v40, v34, v0
	v_mul_f32_e32 v0, 0xbfb8aa3b, v36
	v_exp_f32_e32 v34, v0
	v_mul_f32_e32 v0, 0xbfb8aa3b, v37
	v_exp_f32_e32 v35, v0
	s_nop 0
	v_pk_add_f32 v[34:35], v[34:35], 1.0 op_sel_hi:[1,0]
	s_nop 0
	v_rcp_f32_e32 v0, v35
	v_rcp_f32_e32 v34, v34
	s_nop 0
	v_cvt_pk_bf16_f32 v41, v34, v0
	v_mul_f32_e32 v0, 0xbfb8aa3b, v30
	v_exp_f32_e32 v30, v0
	v_mul_f32_e32 v0, 0xbfb8aa3b, v31
	v_exp_f32_e32 v31, v0
	v_ashrrev_i32_e32 v45, 31, v44
	v_lshlrev_b64 v[34:35], 12, v[44:45]
	v_lshl_add_u64 v[34:35], s[36:37], 0, v[34:35]
	v_pk_add_f32 v[30:31], v[30:31], 1.0 op_sel_hi:[1,0]
	v_lshl_add_u64 v[34:35], v[34:35], 0, v[122:123]
	v_rcp_f32_e32 v0, v31
	global_store_dwordx4 v[34:35], v[38:41], off
	v_rcp_f32_e32 v30, v30
	s_nop 0
	v_cvt_pk_bf16_f32 v30, v30, v0
	v_mul_f32_e32 v0, 0xbfb8aa3b, v32
	v_exp_f32_e32 v32, v0
	v_mul_f32_e32 v0, 0xbfb8aa3b, v33
	v_exp_f32_e32 v33, v0
	s_nop 0
	v_pk_add_f32 v[32:33], v[32:33], 1.0 op_sel_hi:[1,0]
	s_nop 0
	v_rcp_f32_e32 v0, v33
	v_rcp_f32_e32 v31, v32
	s_nop 0
	v_cvt_pk_bf16_f32 v31, v31, v0
	v_mul_f32_e32 v0, 0xbfb8aa3b, v26
	v_exp_f32_e32 v26, v0
	v_mul_f32_e32 v0, 0xbfb8aa3b, v27
	v_exp_f32_e32 v27, v0
	s_nop 0
	v_pk_add_f32 v[26:27], v[26:27], 1.0 op_sel_hi:[1,0]
	s_nop 0
	v_rcp_f32_e32 v0, v27
	v_rcp_f32_e32 v26, v26
	s_nop 0
	v_cvt_pk_bf16_f32 v32, v26, v0
	v_mul_f32_e32 v0, 0xbfb8aa3b, v28
	v_exp_f32_e32 v26, v0
	v_mul_f32_e32 v0, 0xbfb8aa3b, v29
	v_exp_f32_e32 v27, v0
	s_nop 0
	v_pk_add_f32 v[26:27], v[26:27], 1.0 op_sel_hi:[1,0]
; DI unsigned pack2(float a, float b) { f32x2_t v = {a, b}; bf16x2_t r = __builtin_convertvector(v, bf16x2_t); return __builtin_bit_cast(unsigned, r); }
; DI float sigmoidf_(float x) { return 1.f / (1.f + __expf(-x)); }
; DI bfu* wsb(const PX& p, size_t off) { return (bfu*)(p.ws + off); }
; template <int EPI, int HM>
; DI void epi256(const PX& p, int l, f32x4 (&acc)[2][2][4][2], int brow, int bcol, int aux, bool src_input) {
;     ...
;           } else if (EPI == EPI_GATE) {
;             uint4 o;
;             o.x = pack2(sigmoidf_(v[0]), sigmoidf_(v[1])); o.y = pack2(sigmoidf_(v[2]), sigmoidf_(v[3]));
;             o.z = pack2(sigmoidf_(v[4]), sigmoidf_(v[5])); o.w = pack2(sigmoidf_(v[6]), sigmoidf_(v[7]));
;             *(uint4*)(wsb(p, OFF_BIG + B_ZML) + (size_t)row * 2048 + col0) = o;
	s_nop 0
	v_rcp_f32_e32 v0, v27
	v_rcp_f32_e32 v26, v26
	s_nop 0
	v_cvt_pk_bf16_f32 v33, v26, v0
	v_mul_f32_e32 v0, 0xbfb8aa3b, v22
	v_exp_f32_e32 v22, v0
	v_mul_f32_e32 v0, 0xbfb8aa3b, v23
	v_exp_f32_e32 v23, v0
	global_store_dwordx4 v[58:59], v[30:33], off offset:256
	v_pk_add_f32 v[22:23], v[22:23], 1.0 op_sel_hi:[1,0]
	s_nop 0
	v_rcp_f32_e32 v0, v23
	v_rcp_f32_e32 v22, v22
	s_nop 0
	v_cvt_pk_bf16_f32 v22, v22, v0
	v_mul_f32_e32 v0, 0xbfb8aa3b, v24
	v_exp_f32_e32 v24, v0
	v_mul_f32_e32 v0, 0xbfb8aa3b, v25
	v_exp_f32_e32 v25, v0
	s_nop 0
	v_pk_add_f32 v[24:25], v[24:25], 1.0 op_sel_hi:[1,0]
	s_nop 0
	v_rcp_f32_e32 v0, v25
	v_rcp_f32_e32 v23, v24
	s_nop 0
	v_cvt_pk_bf16_f32 v23, v23, v0
	v_mul_f32_e32 v0, 0xbfb8aa3b, v18
	v_exp_f32_e32 v18, v0
	v_mul_f32_e32 v0, 0xbfb8aa3b, v19
	v_exp_f32_e32 v19, v0
	s_nop 0
	v_pk_add_f32 v[18:19], v[18:19], 1.0 op_sel_hi:[1,0]
	s_nop 0
	v_rcp_f32_e32 v0, v19
	v_rcp_f32_e32 v18, v18
	s_nop 0
	v_cvt_pk_bf16_f32 v24, v18, v0
	v_mul_f32_e32 v0, 0xbfb8aa3b, v20
	v_exp_f32_e32 v18, v0
	v_mul_f32_e32 v0, 0xbfb8aa3b, v21
	v_exp_f32_e32 v19, v0
	s_nop 0
	v_pk_add_f32 v[18:19], v[18:19], 1.0 op_sel_hi:[1,0]
	s_nop 0
	v_rcp_f32_e32 v0, v19
	v_rcp_f32_e32 v18, v18
	s_nop 0
	v_cvt_pk_bf16_f32 v25, v18, v0
	v_mul_f32_e32 v0, 0xbfb8aa3b, v14
	v_exp_f32_e32 v14, v0
	v_mul_f32_e32 v0, 0xbfb8aa3b, v15
	v_exp_f32_e32 v15, v0
	global_store_dwordx4 v[50:51], v[22:25], off offset:256
	v_pk_add_f32 v[14:15], v[14:15], 1.0 op_sel_hi:[1,0]
	s_nop 0
	v_rcp_f32_e32 v0, v15
	v_rcp_f32_e32 v14, v14
	s_nop 0
	v_cvt_pk_bf16_f32 v14, v14, v0
	v_mul_f32_e32 v0, 0xbfb8aa3b, v16
	v_exp_f32_e32 v16, v0
	v_mul_f32_e32 v0, 0xbfb8aa3b, v17
	v_exp_f32_e32 v17, v0
	s_nop 0
	v_pk_add_f32 v[16:17], v[16:17], 1.0 op_sel_hi:[1,0]
	s_nop 0
	v_rcp_f32_e32 v0, v17
	v_rcp_f32_e32 v15, v16
	s_nop 0
	v_cvt_pk_bf16_f32 v15, v15, v0
	v_mul_f32_e32 v0, 0xbfb8aa3b, v10
	v_exp_f32_e32 v10, v0
	v_mul_f32_e32 v0, 0xbfb8aa3b, v11
	v_exp_f32_e32 v11, v0
	s_nop 0
	v_pk_add_f32 v[10:11], v[10:11], 1.0 op_sel_hi:[1,0]
	s_nop 0
	v_rcp_f32_e32 v0, v11
	v_rcp_f32_e32 v10, v10
	s_nop 0
	v_cvt_pk_bf16_f32 v16, v10, v0
	v_mul_f32_e32 v0, 0xbfb8aa3b, v12
	v_exp_f32_e32 v10, v0
	v_mul_f32_e32 v0, 0xbfb8aa3b, v13
	v_exp_f32_e32 v11, v0
	s_nop 0
	v_pk_add_f32 v[10:11], v[10:11], 1.0 op_sel_hi:[1,0]
	s_nop 0
	v_rcp_f32_e32 v0, v11
	v_rcp_f32_e32 v10, v10
	s_nop 0
	v_cvt_pk_bf16_f32 v17, v10, v0
	v_mul_f32_e32 v0, 0xbfb8aa3b, v6
	v_exp_f32_e32 v6, v0
	v_mul_f32_e32 v0, 0xbfb8aa3b, v7
	v_exp_f32_e32 v7, v0
	global_store_dwordx4 v[42:43], v[14:17], off offset:256
	v_pk_add_f32 v[6:7], v[6:7], 1.0 op_sel_hi:[1,0]
	s_nop 0
	v_rcp_f32_e32 v0, v7
	v_rcp_f32_e32 v6, v6
	s_nop 0
	v_cvt_pk_bf16_f32 v6, v6, v0
	v_mul_f32_e32 v0, 0xbfb8aa3b, v8
	v_exp_f32_e32 v8, v0
	v_mul_f32_e32 v0, 0xbfb8aa3b, v9
	v_exp_f32_e32 v9, v0
	s_nop 0
	v_pk_add_f32 v[8:9], v[8:9], 1.0 op_sel_hi:[1,0]
	s_nop 0
	v_rcp_f32_e32 v0, v9
	v_rcp_f32_e32 v7, v8
	s_nop 0
	v_cvt_pk_bf16_f32 v7, v7, v0
	v_mul_f32_e32 v0, 0xbfb8aa3b, v2
	v_exp_f32_e32 v2, v0
	v_mul_f32_e32 v0, 0xbfb8aa3b, v3
	v_exp_f32_e32 v3, v0
	s_nop 0
	v_pk_add_f32 v[2:3], v[2:3], 1.0 op_sel_hi:[1,0]
	s_nop 0
	v_rcp_f32_e32 v0, v3
	v_rcp_f32_e32 v2, v2
	s_nop 0
	v_cvt_pk_bf16_f32 v8, v2, v0
	v_mul_f32_e32 v0, 0xbfb8aa3b, v4
	v_exp_f32_e32 v2, v0
	v_mul_f32_e32 v0, 0xbfb8aa3b, v5
	v_exp_f32_e32 v3, v0
	s_nop 0
	v_pk_add_f32 v[2:3], v[2:3], 1.0 op_sel_hi:[1,0]
	s_nop 0
	v_rcp_f32_e32 v0, v3
	v_rcp_f32_e32 v2, v2
	s_nop 0
	v_cvt_pk_bf16_f32 v9, v2, v0
	global_store_dwordx4 v[34:35], v[6:9], off offset:256
	s_nop 0
	v_ashrrev_i32_e32 v0, 8, v144
	v_cmp_eq_u32_e32 vcc, 1, v0
	s_and_saveexec_b64 s[76:77], vcc
	s_cbranch_execz .LBB0_309
	s_barrier

; DI unsigned pack2(float a, float b) { f32x2_t v = {a, b}; bf16x2_t r = __builtin_convertvector(v, bf16x2_t); return __builtin_bit_cast(unsigned, r); }
; DI float lo16(unsigned u) { return __uint_as_float(u << 16); }
; DI float hi16(unsigned u) { return __uint_as_float(u & 0xffff0000u); }
; DI float sigmoidf_(float x) { return 1.f / (1.f + __expf(-x)); }
; DI bfu* wsb(const PX& p, size_t off) { return (bfu*)(p.ws + off); }
; template <int EPI, int HM>
; DI void epi256(const PX& p, int l, f32x4 (&acc)[2][2][4][2], int brow, int bcol, int aux, bool src_input) {
;     ...
;           } else if (EPI == EPI_GLU) {
;             const float* gbp = p.in[30] + l * 768 + col0;
;             const f32x4 g0 = *(const f32x4*)gbp, g1 = *(const f32x4*)(gbp + 4);
;             const float gb[8] = {g0[0], g0[1], g0[2], g0[3], g1[0], g1[1], g1[2], g1[3]};
;             const uint4 z = *(const uint4*)(wsb(p, OFF_BIG + B_YF) + (size_t)row * 768 + col0);
;             const unsigned zz[4] = {z.x, z.y, z.z, z.w};
;             unsigned oo[4];
; #pragma unroll
;             for (int q = 0; q < 4; q++)
;               oo[q] = pack2(lo16(zz[q]) * sigmoidf_(v[2 * q] + gb[2 * q]), hi16(zz[q]) * sigmoidf_(v[2 * q + 1] + gb[2 * q + 1]));
;             *(uint4*)(wsb(p, OFF_BIG + B_YB) + (size_t)row * 768 + col0) = make_uint4(oo[0], oo[1], oo[2], oo[3]);
.LBB0_354:
	s_or_b64 exec, exec, s[10:11]
	v_mov_b32_e32 v130, v188
	s_nop 0
	v_ashrrev_i32_e32 v0, 2, v130
	v_and_or_b32 v131, v130, 15, s1
	v_lshrrev_b32_e32 v130, 1, v130
	v_and_b32_e32 v130, 0x78, v130
	v_or_b32_e32 v132, s0, v130
	v_and_b32_e32 v0, 0xffffffc0, v0
	v_ashrrev_i32_e32 v133, 31, v132
	v_add_u32_e32 v0, v131, v0
	v_lshl_add_u64 v[130:131], v[132:133], 2, s[6:7]
	global_load_dwordx4 v[138:141], v[130:131], off offset:16
	global_load_dwordx4 v[142:145], v[130:131], off
	v_readlane_b32 s0, v254, 4
	v_readlane_b32 s1, v254, 5
	v_lshlrev_b64 v[132:133], 1, v[132:133]
	s_waitcnt vmcnt(0)
	v_add_f32_e32 v122, v122, v138
	v_mov_b64_e32 v[134:135], s[0:1]
	v_mad_i64_i32 v[136:137], s[0:1], v0, s81, v[134:135]
	v_lshl_add_u64 v[136:137], v[136:137], 0, v[132:133]
	global_load_dwordx4 v[146:149], v[136:137], off
	v_add_f32_e32 v126, v126, v142
	v_add_f32_e32 v127, v127, v143
	v_mul_f32_e32 v126, 0xbfb8aa3b, v126
	v_mul_f32_e32 v127, 0xbfb8aa3b, v127
	v_exp_f32_e32 v126, v126
	v_exp_f32_e32 v127, v127
	v_add_f32_e32 v129, v129, v145
	v_mul_f32_e32 v129, 0xbfb8aa3b, v129
	v_exp_f32_e32 v129, v129
	v_pk_add_f32 v[126:127], v[126:127], 1.0 op_sel_hi:[1,0]
	v_add_f32_e32 v123, v123, v139
	v_rcp_f32_e32 v127, v127
	v_mul_f32_e32 v122, 0xbfb8aa3b, v122
	v_mul_f32_e32 v123, 0xbfb8aa3b, v123
	v_exp_f32_e32 v122, v122
	v_exp_f32_e32 v123, v123
	v_add_f32_e32 v125, v125, v141
	v_mul_f32_e32 v125, 0xbfb8aa3b, v125
	v_exp_f32_e32 v125, v125
	v_pk_add_f32 v[122:123], v[122:123], 1.0 op_sel_hi:[1,0]
	s_waitcnt vmcnt(0)
	v_lshlrev_b32_e32 v150, 16, v146
	v_and_b32_e32 v151, 0xffff0000, v146
	v_rcp_f32_e32 v126, v126
	s_nop 0
	v_pk_mul_f32 v[126:127], v[126:127], v[150:151]
	v_or_b32_e32 v150, 16, v0
	v_cvt_pk_bf16_f32 v142, v126, v127
	v_add_f32_e32 v127, v128, v144
	v_mul_f32_e32 v127, 0xbfb8aa3b, v127
	v_exp_f32_e32 v128, v127
	v_lshlrev_b32_e32 v126, 16, v147
	v_and_b32_e32 v127, 0xffff0000, v147
	v_pk_add_f32 v[128:129], v[128:129], 1.0 op_sel_hi:[1,0]
	s_nop 0
	v_rcp_f32_e32 v129, v129
	v_rcp_f32_e32 v128, v128
	s_nop 0
	v_pk_mul_f32 v[126:127], v[128:129], v[126:127]
	v_rcp_f32_e32 v123, v123
	v_cvt_pk_bf16_f32 v143, v126, v127
	v_lshlrev_b32_e32 v126, 16, v148
	v_and_b32_e32 v127, 0xffff0000, v148
	v_rcp_f32_e32 v122, v122
	s_nop 0
	v_pk_mul_f32 v[122:123], v[122:123], v[126:127]
	s_nop 0
	v_cvt_pk_bf16_f32 v144, v122, v123
	v_add_f32_e32 v123, v124, v140
	v_mul_f32_e32 v123, 0xbfb8aa3b, v123
	v_exp_f32_e32 v124, v123
	v_lshlrev_b32_e32 v122, 16, v149
	v_and_b32_e32 v123, 0xffff0000, v149
	v_pk_add_f32 v[124:125], v[124:125], 1.0 op_sel_hi:[1,0]
	s_nop 0
	v_rcp_f32_e32 v125, v125
	v_rcp_f32_e32 v124, v124
	v_readlane_b32 s0, v254, 6
	v_readlane_b32 s1, v254, 7
	v_pk_mul_f32 v[122:123], v[124:125], v[122:123]
	s_nop 0
	v_cvt_pk_bf16_f32 v145, v122, v123
	v_mov_b64_e32 v[122:123], s[0:1]
	v_mad_i64_i32 v[124:125], s[0:1], v0, s81, v[122:123]
	v_lshl_add_u64 v[126:127], v[124:125], 0, v[132:133]
	global_store_dwordx4 v[126:127], v[142:145], off
	global_load_dwordx4 v[138:141], v[130:131], off offset:16
	s_nop 0
	global_load_dwordx4 v[142:145], v[130:131], off
	v_mad_i64_i32 v[124:125], s[0:1], v150, s81, v[134:135]
	v_lshl_add_u64 v[124:125], v[124:125], 0, v[132:133]
	global_load_dwordx4 v[146:149], v[124:125], off
	s_waitcnt vmcnt(0)
	v_add_f32_e32 v114, v114, v138
	v_add_f32_e32 v118, v118, v142
	v_add_f32_e32 v119, v119, v143
	v_mul_f32_e32 v118, 0xbfb8aa3b, v118
	v_mul_f32_e32 v119, 0xbfb8aa3b, v119
	v_exp_f32_e32 v118, v118
	v_exp_f32_e32 v119, v119
	v_lshlrev_b32_e32 v128, 16, v146
	v_and_b32_e32 v129, 0xffff0000, v146
	v_add_f32_e32 v115, v115, v139
	v_pk_add_f32 v[118:119], v[118:119], 1.0 op_sel_hi:[1,0]
	v_mul_f32_e32 v114, 0xbfb8aa3b, v114
	v_rcp_f32_e32 v119, v119
	v_mul_f32_e32 v115, 0xbfb8aa3b, v115
	v_exp_f32_e32 v114, v114
	v_exp_f32_e32 v115, v115
	s_nop 0
	v_rcp_f32_e32 v118, v118
	v_pk_add_f32 v[114:115], v[114:115], 1.0 op_sel_hi:[1,0]
	v_add_f32_e32 v117, v117, v141
	v_mul_f32_e32 v117, 0xbfb8aa3b, v117
	v_pk_mul_f32 v[118:119], v[118:119], v[128:129]
	v_lshlrev_b32_e32 v128, 16, v147
	v_cvt_pk_bf16_f32 v118, v118, v119
	v_add_f32_e32 v119, v120, v144
	v_mul_f32_e32 v119, 0xbfb8aa3b, v119
	v_exp_f32_e32 v120, v119
	v_add_f32_e32 v119, v121, v145
	v_mul_f32_e32 v119, 0xbfb8aa3b, v119
	v_exp_f32_e32 v121, v119
	v_and_b32_e32 v129, 0xffff0000, v147
	v_exp_f32_e32 v117, v117
	v_or_b32_e32 v146, 32, v0
	v_pk_add_f32 v[120:121], v[120:121], 1.0 op_sel_hi:[1,0]
	s_nop 0
	v_rcp_f32_e32 v121, v121
	v_rcp_f32_e32 v120, v120
	s_nop 0
	v_pk_mul_f32 v[120:121], v[120:121], v[128:129]
	v_rcp_f32_e32 v115, v115
	v_cvt_pk_bf16_f32 v119, v120, v121
	v_lshlrev_b32_e32 v120, 16, v148
	v_and_b32_e32 v121, 0xffff0000, v148
	v_rcp_f32_e32 v114, v114
	s_nop 0
	v_pk_mul_f32 v[114:115], v[114:115], v[120:121]
	s_nop 0
	v_cvt_pk_bf16_f32 v120, v114, v115
	v_add_f32_e32 v115, v116, v140
	v_mul_f32_e32 v115, 0xbfb8aa3b, v115
	v_exp_f32_e32 v116, v115
	v_lshlrev_b32_e32 v114, 16, v149
	v_and_b32_e32 v115, 0xffff0000, v149
	v_pk_add_f32 v[116:117], v[116:117], 1.0 op_sel_hi:[1,0]
	s_nop 0
	v_rcp_f32_e32 v117, v117
	v_rcp_f32_e32 v116, v116
	s_nop 0
	v_pk_mul_f32 v[114:115], v[116:117], v[114:115]
	s_nop 0
	v_cvt_pk_bf16_f32 v121, v114, v115
	v_mad_i64_i32 v[114:115], s[0:1], v150, s81, v[122:123]
	v_lshl_add_u64 v[116:117], v[114:115], 0, v[132:133]
	global_store_dwordx4 v[116:117], v[118:121], off
	global_load_dwordx4 v[118:121], v[130:131], off offset:16
	s_nop 0
	global_load_dwordx4 v[138:141], v[130:131], off
	v_mad_i64_i32 v[114:115], s[0:1], v146, s81, v[134:135]
	v_lshl_add_u64 v[114:115], v[114:115], 0, v[132:133]
	global_load_dwordx4 v[142:145], v[114:115], off
	s_waitcnt vmcnt(0)
; DI unsigned pack2(float a, float b) { f32x2_t v = {a, b}; bf16x2_t r = __builtin_convertvector(v, bf16x2_t); return __builtin_bit_cast(unsigned, r); }
; DI float lo16(unsigned u) { return __uint_as_float(u << 16); }
; DI float hi16(unsigned u) { return __uint_as_float(u & 0xffff0000u); }
; DI float sigmoidf_(float x) { return 1.f / (1.f + __expf(-x)); }
; DI bfu* wsb(const PX& p, size_t off) { return (bfu*)(p.ws + off); }
; template <int EPI, int HM>
; DI void epi256(const PX& p, int l, f32x4 (&acc)[2][2][4][2], int brow, int bcol, int aux, bool src_input) {
;     ...
;           } else if (EPI == EPI_GLU) {
;             const float* gbp = p.in[30] + l * 768 + col0;
;             const f32x4 g0 = *(const f32x4*)gbp, g1 = *(const f32x4*)(gbp + 4);
;             const float gb[8] = {g0[0], g0[1], g0[2], g0[3], g1[0], g1[1], g1[2], g1[3]};
;             const uint4 z = *(const uint4*)(wsb(p, OFF_BIG + B_YF) + (size_t)row * 768 + col0);
;             const unsigned zz[4] = {z.x, z.y, z.z, z.w};
;             unsigned oo[4];
; #pragma unroll
;             for (int q = 0; q < 4; q++)
;               oo[q] = pack2(lo16(zz[q]) * sigmoidf_(v[2 * q] + gb[2 * q]), hi16(zz[q]) * sigmoidf_(v[2 * q + 1] + gb[2 * q + 1]));
;             *(uint4*)(wsb(p, OFF_BIG + B_YB) + (size_t)row * 768 + col0) = make_uint4(oo[0], oo[1], oo[2], oo[3]);
	v_add_f32_e32 v106, v106, v118
	v_add_f32_e32 v110, v110, v138
	v_add_f32_e32 v111, v111, v139
	v_mul_f32_e32 v110, 0xbfb8aa3b, v110
	v_mul_f32_e32 v111, 0xbfb8aa3b, v111
	v_exp_f32_e32 v110, v110
	v_exp_f32_e32 v111, v111
	v_lshlrev_b32_e32 v128, 16, v142
	v_and_b32_e32 v129, 0xffff0000, v142
	v_add_f32_e32 v113, v113, v141
	v_pk_add_f32 v[110:111], v[110:111], 1.0 op_sel_hi:[1,0]
	v_mul_f32_e32 v113, 0xbfb8aa3b, v113
	v_rcp_f32_e32 v111, v111
	v_exp_f32_e32 v113, v113
	v_add_f32_e32 v107, v107, v119
	v_mul_f32_e32 v106, 0xbfb8aa3b, v106
	v_rcp_f32_e32 v110, v110
	v_mul_f32_e32 v107, 0xbfb8aa3b, v107
	v_exp_f32_e32 v106, v106
	v_exp_f32_e32 v107, v107
	s_nop 0
	v_pk_mul_f32 v[110:111], v[110:111], v[128:129]
	v_pk_add_f32 v[106:107], v[106:107], 1.0 op_sel_hi:[1,0]
	v_cvt_pk_bf16_f32 v138, v110, v111
	v_add_f32_e32 v111, v112, v140
	v_mul_f32_e32 v111, 0xbfb8aa3b, v111
	v_exp_f32_e32 v112, v111
	v_lshlrev_b32_e32 v110, 16, v143
	v_and_b32_e32 v111, 0xffff0000, v143
	v_add_f32_e32 v109, v109, v121
	v_pk_add_f32 v[112:113], v[112:113], 1.0 op_sel_hi:[1,0]
	v_mul_f32_e32 v109, 0xbfb8aa3b, v109
	v_rcp_f32_e32 v113, v113
	v_exp_f32_e32 v109, v109
	s_nop 0
	v_rcp_f32_e32 v112, v112
	s_nop 0
	v_pk_mul_f32 v[110:111], v[112:113], v[110:111]
	v_rcp_f32_e32 v107, v107
	v_cvt_pk_bf16_f32 v139, v110, v111
	v_lshlrev_b32_e32 v110, 16, v144
	v_and_b32_e32 v111, 0xffff0000, v144
	v_rcp_f32_e32 v106, v106
	s_nop 0
	v_pk_mul_f32 v[106:107], v[106:107], v[110:111]
	s_nop 0
	v_cvt_pk_bf16_f32 v140, v106, v107
	v_add_f32_e32 v107, v108, v120
	v_mul_f32_e32 v107, 0xbfb8aa3b, v107
	v_exp_f32_e32 v108, v107
	v_lshlrev_b32_e32 v106, 16, v145
	v_and_b32_e32 v107, 0xffff0000, v145
	v_pk_add_f32 v[108:109], v[108:109], 1.0 op_sel_hi:[1,0]
	s_nop 0
	v_rcp_f32_e32 v109, v109
	v_rcp_f32_e32 v108, v108
	s_nop 0
	v_pk_mul_f32 v[106:107], v[108:109], v[106:107]
	v_or_b32_e32 v112, 48, v0
	v_cvt_pk_bf16_f32 v141, v106, v107
	v_mad_i64_i32 v[106:107], s[0:1], v146, s81, v[122:123]
	v_lshl_add_u64 v[110:111], v[106:107], 0, v[132:133]
	global_store_dwordx4 v[110:111], v[138:141], off
	global_load_dwordx4 v[118:121], v[130:131], off offset:16
	s_nop 0
	global_load_dwordx4 v[138:141], v[130:131], off
	v_mad_i64_i32 v[106:107], s[0:1], v112, s81, v[134:135]
	v_lshl_add_u64 v[108:109], v[106:107], 0, v[132:133]
	global_load_dwordx4 v[142:145], v[108:109], off
	s_waitcnt vmcnt(0)
	v_add_f32_e32 v98, v98, v118
	v_add_f32_e32 v102, v102, v138
	v_add_f32_e32 v103, v103, v139
	v_mul_f32_e32 v102, 0xbfb8aa3b, v102
	v_mul_f32_e32 v103, 0xbfb8aa3b, v103
	v_exp_f32_e32 v102, v102
	v_exp_f32_e32 v103, v103
	v_lshlrev_b32_e32 v106, 16, v142
	v_and_b32_e32 v107, 0xffff0000, v142
	v_add_f32_e32 v99, v99, v119
	v_pk_add_f32 v[102:103], v[102:103], 1.0 op_sel_hi:[1,0]
	v_mul_f32_e32 v98, 0xbfb8aa3b, v98
	v_rcp_f32_e32 v103, v103
	v_mul_f32_e32 v99, 0xbfb8aa3b, v99
	v_exp_f32_e32 v98, v98
	v_exp_f32_e32 v99, v99
	s_nop 0
	v_rcp_f32_e32 v102, v102
	v_pk_add_f32 v[98:99], v[98:99], 1.0 op_sel_hi:[1,0]
	v_add_f32_e32 v101, v101, v121
	v_mul_f32_e32 v101, 0xbfb8aa3b, v101
	v_pk_mul_f32 v[102:103], v[102:103], v[106:107]
	v_lshlrev_b32_e32 v106, 16, v143
	v_cvt_pk_bf16_f32 v102, v102, v103
	v_add_f32_e32 v103, v104, v140
	v_mul_f32_e32 v103, 0xbfb8aa3b, v103
	v_exp_f32_e32 v104, v103
	v_add_f32_e32 v103, v105, v141
	v_mul_f32_e32 v103, 0xbfb8aa3b, v103
	v_exp_f32_e32 v105, v103
	v_and_b32_e32 v107, 0xffff0000, v143
	v_exp_f32_e32 v101, v101
	v_pk_add_f32 v[104:105], v[104:105], 1.0 op_sel_hi:[1,0]
	s_nop 0
	v_rcp_f32_e32 v105, v105
	v_rcp_f32_e32 v104, v104
	s_nop 0
	v_pk_mul_f32 v[104:105], v[104:105], v[106:107]
	v_rcp_f32_e32 v99, v99
	v_cvt_pk_bf16_f32 v103, v104, v105
	v_lshlrev_b32_e32 v104, 16, v144
	v_and_b32_e32 v105, 0xffff0000, v144
	v_rcp_f32_e32 v98, v98
	s_nop 0
	v_pk_mul_f32 v[98:99], v[98:99], v[104:105]
	s_nop 0
	v_cvt_pk_bf16_f32 v104, v98, v99
	v_add_f32_e32 v99, v100, v120
	v_mul_f32_e32 v99, 0xbfb8aa3b, v99
	v_exp_f32_e32 v100, v99
	v_lshlrev_b32_e32 v98, 16, v145
	v_and_b32_e32 v99, 0xffff0000, v145
	v_pk_add_f32 v[100:101], v[100:101], 1.0 op_sel_hi:[1,0]
	s_nop 0
	v_rcp_f32_e32 v101, v101
	v_rcp_f32_e32 v100, v100
	s_nop 0
	v_pk_mul_f32 v[98:99], v[100:101], v[98:99]
	s_nop 0
	v_cvt_pk_bf16_f32 v105, v98, v99
	v_mad_i64_i32 v[98:99], s[0:1], v112, s81, v[122:123]
	v_lshl_add_u64 v[106:107], v[98:99], 0, v[132:133]
	global_store_dwordx4 v[106:107], v[102:105], off
	global_load_dwordx4 v[98:101], v[130:131], off offset:528
	s_nop 0
	global_load_dwordx4 v[102:105], v[130:131], off offset:512
	global_load_dwordx4 v[118:121], v[136:137], off offset:256
	s_waitcnt vmcnt(0)
; DI unsigned pack2(float a, float b) { f32x2_t v = {a, b}; bf16x2_t r = __builtin_convertvector(v, bf16x2_t); return __builtin_bit_cast(unsigned, r); }
; DI float lo16(unsigned u) { return __uint_as_float(u << 16); }
; DI float hi16(unsigned u) { return __uint_as_float(u & 0xffff0000u); }
; DI float sigmoidf_(float x) { return 1.f / (1.f + __expf(-x)); }
; DI bfu* wsb(const PX& p, size_t off) { return (bfu*)(p.ws + off); }
; template <int EPI, int HM>
; DI void epi256(const PX& p, int l, f32x4 (&acc)[2][2][4][2], int brow, int bcol, int aux, bool src_input) {
;     ...
;           } else if (EPI == EPI_GLU) {
;             const float* gbp = p.in[30] + l * 768 + col0;
;             const f32x4 g0 = *(const f32x4*)gbp, g1 = *(const f32x4*)(gbp + 4);
;             const float gb[8] = {g0[0], g0[1], g0[2], g0[3], g1[0], g1[1], g1[2], g1[3]};
;             const uint4 z = *(const uint4*)(wsb(p, OFF_BIG + B_YF) + (size_t)row * 768 + col0);
;             const unsigned zz[4] = {z.x, z.y, z.z, z.w};
;             unsigned oo[4];
; #pragma unroll
;             for (int q = 0; q < 4; q++)
;               oo[q] = pack2(lo16(zz[q]) * sigmoidf_(v[2 * q] + gb[2 * q]), hi16(zz[q]) * sigmoidf_(v[2 * q + 1] + gb[2 * q + 1]));
;             *(uint4*)(wsb(p, OFF_BIG + B_YB) + (size_t)row * 768 + col0) = make_uint4(oo[0], oo[1], oo[2], oo[3]);
	v_add_f32_e32 v90, v90, v98
	v_add_f32_e32 v94, v94, v102
	v_add_f32_e32 v95, v95, v103
	v_mul_f32_e32 v94, 0xbfb8aa3b, v94
	v_mul_f32_e32 v95, 0xbfb8aa3b, v95
	v_exp_f32_e32 v94, v94
	v_exp_f32_e32 v95, v95
	v_lshlrev_b32_e32 v112, 16, v118
	v_and_b32_e32 v113, 0xffff0000, v118
	v_add_f32_e32 v91, v91, v99
	v_pk_add_f32 v[94:95], v[94:95], 1.0 op_sel_hi:[1,0]
	v_mul_f32_e32 v90, 0xbfb8aa3b, v90
	v_rcp_f32_e32 v95, v95
	v_mul_f32_e32 v91, 0xbfb8aa3b, v91
	v_exp_f32_e32 v90, v90
	v_exp_f32_e32 v91, v91
	s_nop 0
	v_rcp_f32_e32 v94, v94
	v_pk_add_f32 v[90:91], v[90:91], 1.0 op_sel_hi:[1,0]
	v_add_f32_e32 v93, v93, v101
	v_pk_mul_f32 v[94:95], v[94:95], v[112:113]
	v_rcp_f32_e32 v91, v91
	v_cvt_pk_bf16_f32 v94, v94, v95
	v_add_f32_e32 v95, v96, v104
	v_mul_f32_e32 v95, 0xbfb8aa3b, v95
	v_exp_f32_e32 v96, v95
	v_add_f32_e32 v95, v97, v105
	v_mul_f32_e32 v95, 0xbfb8aa3b, v95
	v_exp_f32_e32 v97, v95
	v_lshlrev_b32_e32 v102, 16, v119
	v_and_b32_e32 v103, 0xffff0000, v119
	v_mul_f32_e32 v93, 0xbfb8aa3b, v93
	v_pk_add_f32 v[96:97], v[96:97], 1.0 op_sel_hi:[1,0]
	v_exp_f32_e32 v93, v93
	s_nop 0
	v_rcp_f32_e32 v97, v97
	v_rcp_f32_e32 v96, v96
	s_nop 0
	v_pk_mul_f32 v[96:97], v[96:97], v[102:103]
	v_rcp_f32_e32 v90, v90
	v_cvt_pk_bf16_f32 v95, v96, v97
	v_lshlrev_b32_e32 v96, 16, v120
	v_and_b32_e32 v97, 0xffff0000, v120
	v_pk_mul_f32 v[90:91], v[90:91], v[96:97]
	s_nop 0
	v_cvt_pk_bf16_f32 v96, v90, v91
	v_add_f32_e32 v91, v92, v100
	v_mul_f32_e32 v91, 0xbfb8aa3b, v91
	v_exp_f32_e32 v92, v91
	v_lshlrev_b32_e32 v90, 16, v121
	v_and_b32_e32 v91, 0xffff0000, v121
	v_pk_add_f32 v[92:93], v[92:93], 1.0 op_sel_hi:[1,0]
	s_nop 0
	v_rcp_f32_e32 v93, v93
	v_rcp_f32_e32 v92, v92
	s_nop 0
	v_pk_mul_f32 v[90:91], v[92:93], v[90:91]
	s_nop 0
	v_cvt_pk_bf16_f32 v97, v90, v91
	global_store_dwordx4 v[126:127], v[94:97], off offset:256
	global_load_dwordx4 v[90:93], v[130:131], off offset:528
	s_nop 0
	global_load_dwordx4 v[94:97], v[130:131], off offset:512
	global_load_dwordx4 v[98:101], v[124:125], off offset:256
	s_waitcnt vmcnt(0)
	v_add_f32_e32 v82, v82, v90
	v_add_f32_e32 v86, v86, v94
	v_add_f32_e32 v87, v87, v95
	v_mul_f32_e32 v86, 0xbfb8aa3b, v86
	v_mul_f32_e32 v87, 0xbfb8aa3b, v87
	v_exp_f32_e32 v86, v86
	v_exp_f32_e32 v87, v87
	v_lshlrev_b32_e32 v102, 16, v98
	v_and_b32_e32 v103, 0xffff0000, v98
	v_add_f32_e32 v83, v83, v91
	v_pk_add_f32 v[86:87], v[86:87], 1.0 op_sel_hi:[1,0]
	v_mul_f32_e32 v82, 0xbfb8aa3b, v82
	v_rcp_f32_e32 v87, v87
	v_mul_f32_e32 v83, 0xbfb8aa3b, v83
	v_exp_f32_e32 v82, v82
	v_exp_f32_e32 v83, v83
	s_nop 0
	v_rcp_f32_e32 v86, v86
	v_pk_add_f32 v[82:83], v[82:83], 1.0 op_sel_hi:[1,0]
	v_add_f32_e32 v85, v85, v93
	v_pk_mul_f32 v[86:87], v[86:87], v[102:103]
	v_lshlrev_b32_e32 v94, 16, v99
	v_cvt_pk_bf16_f32 v86, v86, v87
	v_add_f32_e32 v87, v88, v96
	v_mul_f32_e32 v87, 0xbfb8aa3b, v87
	v_exp_f32_e32 v88, v87
	v_add_f32_e32 v87, v89, v97
	v_mul_f32_e32 v87, 0xbfb8aa3b, v87
	v_exp_f32_e32 v89, v87
	v_and_b32_e32 v95, 0xffff0000, v99
	v_rcp_f32_e32 v83, v83
	v_mul_f32_e32 v85, 0xbfb8aa3b, v85
	v_pk_add_f32 v[88:89], v[88:89], 1.0 op_sel_hi:[1,0]
	v_exp_f32_e32 v85, v85
	s_nop 0
	v_rcp_f32_e32 v89, v89
	v_rcp_f32_e32 v88, v88
	s_nop 0
	v_pk_mul_f32 v[88:89], v[88:89], v[94:95]
	v_rcp_f32_e32 v82, v82
	v_cvt_pk_bf16_f32 v87, v88, v89
	v_lshlrev_b32_e32 v88, 16, v100
	v_and_b32_e32 v89, 0xffff0000, v100
	v_pk_mul_f32 v[82:83], v[82:83], v[88:89]
	s_nop 0
	v_cvt_pk_bf16_f32 v88, v82, v83
	v_add_f32_e32 v83, v84, v92
	v_mul_f32_e32 v83, 0xbfb8aa3b, v83
	v_exp_f32_e32 v84, v83
	v_lshlrev_b32_e32 v82, 16, v101
	v_and_b32_e32 v83, 0xffff0000, v101
	v_pk_add_f32 v[84:85], v[84:85], 1.0 op_sel_hi:[1,0]
	s_nop 0
	v_rcp_f32_e32 v85, v85
	v_rcp_f32_e32 v84, v84
	s_nop 0
	v_pk_mul_f32 v[82:83], v[84:85], v[82:83]
	s_nop 0
	v_cvt_pk_bf16_f32 v89, v82, v83
	global_store_dwordx4 v[116:117], v[86:89], off offset:256
	global_load_dwordx4 v[82:85], v[130:131], off offset:528
	s_nop 0
	global_load_dwordx4 v[86:89], v[130:131], off offset:512
	global_load_dwordx4 v[90:93], v[114:115], off offset:256
	s_waitcnt vmcnt(0)
	v_add_f32_e32 v74, v74, v82
	v_add_f32_e32 v78, v78, v86
	v_add_f32_e32 v79, v79, v87
	v_mul_f32_e32 v78, 0xbfb8aa3b, v78
	v_mul_f32_e32 v79, 0xbfb8aa3b, v79
	v_exp_f32_e32 v78, v78
	v_exp_f32_e32 v79, v79
	v_lshlrev_b32_e32 v94, 16, v90
	v_and_b32_e32 v95, 0xffff0000, v90
	v_add_f32_e32 v75, v75, v83
	v_pk_add_f32 v[78:79], v[78:79], 1.0 op_sel_hi:[1,0]
	v_mul_f32_e32 v74, 0xbfb8aa3b, v74
	v_rcp_f32_e32 v79, v79
	v_mul_f32_e32 v75, 0xbfb8aa3b, v75
	v_exp_f32_e32 v74, v74
	v_exp_f32_e32 v75, v75
	s_nop 0
	v_rcp_f32_e32 v78, v78
	v_pk_add_f32 v[74:75], v[74:75], 1.0 op_sel_hi:[1,0]
	v_add_f32_e32 v77, v77, v85
	v_pk_mul_f32 v[78:79], v[78:79], v[94:95]
	v_lshlrev_b32_e32 v86, 16, v91
	v_cvt_pk_bf16_f32 v78, v78, v79
	v_add_f32_e32 v79, v80, v88
	v_mul_f32_e32 v79, 0xbfb8aa3b, v79
	v_exp_f32_e32 v80, v79
	v_add_f32_e32 v79, v81, v89
	v_mul_f32_e32 v79, 0xbfb8aa3b, v79
	v_exp_f32_e32 v81, v79
	v_and_b32_e32 v87, 0xffff0000, v91
	v_rcp_f32_e32 v75, v75
	v_mul_f32_e32 v77, 0xbfb8aa3b, v77
	v_pk_add_f32 v[80:81], v[80:81], 1.0 op_sel_hi:[1,0]
	v_exp_f32_e32 v77, v77
	s_nop 0
	v_rcp_f32_e32 v81, v81
	v_rcp_f32_e32 v80, v80
	s_nop 0
	v_pk_mul_f32 v[80:81], v[80:81], v[86:87]
	v_rcp_f32_e32 v74, v74
	v_cvt_pk_bf16_f32 v79, v80, v81
	v_lshlrev_b32_e32 v80, 16, v92
	v_and_b32_e32 v81, 0xffff0000, v92
	v_pk_mul_f32 v[74:75], v[74:75], v[80:81]
	s_nop 0
	v_cvt_pk_bf16_f32 v80, v74, v75
	v_add_f32_e32 v75, v76, v84
	v_mul_f32_e32 v75, 0xbfb8aa3b, v75
	v_exp_f32_e32 v76, v75
	v_lshlrev_b32_e32 v74, 16, v93
	v_and_b32_e32 v75, 0xffff0000, v93
	v_pk_add_f32 v[76:77], v[76:77], 1.0 op_sel_hi:[1,0]
	s_nop 0
	v_rcp_f32_e32 v77, v77
	v_rcp_f32_e32 v76, v76
	s_nop 0
	v_pk_mul_f32 v[74:75], v[76:77], v[74:75]
	s_nop 0
	v_cvt_pk_bf16_f32 v81, v74, v75
	global_store_dwordx4 v[110:111], v[78:81], off offset:256
	global_load_dwordx4 v[74:77], v[130:131], off offset:528
	s_nop 0
	global_load_dwordx4 v[78:81], v[130:131], off offset:512
	global_load_dwordx4 v[82:85], v[108:109], off offset:256
	s_waitcnt vmcnt(0)
; DI unsigned pack2(float a, float b) { f32x2_t v = {a, b}; bf16x2_t r = __builtin_convertvector(v, bf16x2_t); return __builtin_bit_cast(unsigned, r); }
; DI float lo16(unsigned u) { return __uint_as_float(u << 16); }
; DI float hi16(unsigned u) { return __uint_as_float(u & 0xffff0000u); }
; DI float sigmoidf_(float x) { return 1.f / (1.f + __expf(-x)); }
; DI bfu* wsb(const PX& p, size_t off) { return (bfu*)(p.ws + off); }
; template <int EPI, int HM>
; DI void epi256(const PX& p, int l, f32x4 (&acc)[2][2][4][2], int brow, int bcol, int aux, bool src_input) {
;     ...
;           } else if (EPI == EPI_GLU) {
;             const float* gbp = p.in[30] + l * 768 + col0;
;             const f32x4 g0 = *(const f32x4*)gbp, g1 = *(const f32x4*)(gbp + 4);
;             const float gb[8] = {g0[0], g0[1], g0[2], g0[3], g1[0], g1[1], g1[2], g1[3]};
;             const uint4 z = *(const uint4*)(wsb(p, OFF_BIG + B_YF) + (size_t)row * 768 + col0);
;             const unsigned zz[4] = {z.x, z.y, z.z, z.w};
;             unsigned oo[4];
; #pragma unroll
;             for (int q = 0; q < 4; q++)
;               oo[q] = pack2(lo16(zz[q]) * sigmoidf_(v[2 * q] + gb[2 * q]), hi16(zz[q]) * sigmoidf_(v[2 * q + 1] + gb[2 * q + 1]));
;             *(uint4*)(wsb(p, OFF_BIG + B_YB) + (size_t)row * 768 + col0) = make_uint4(oo[0], oo[1], oo[2], oo[3]);
	v_add_f32_e32 v66, v66, v74
	v_add_f32_e32 v70, v70, v78
	v_add_f32_e32 v71, v71, v79
	v_mul_f32_e32 v70, 0xbfb8aa3b, v70
	v_mul_f32_e32 v71, 0xbfb8aa3b, v71
	v_exp_f32_e32 v70, v70
	v_exp_f32_e32 v71, v71
	v_lshlrev_b32_e32 v86, 16, v82
	v_and_b32_e32 v87, 0xffff0000, v82
	v_add_f32_e32 v67, v67, v75
	v_pk_add_f32 v[70:71], v[70:71], 1.0 op_sel_hi:[1,0]
	v_mul_f32_e32 v66, 0xbfb8aa3b, v66
	v_rcp_f32_e32 v71, v71
	v_mul_f32_e32 v67, 0xbfb8aa3b, v67
	v_exp_f32_e32 v66, v66
	v_exp_f32_e32 v67, v67
	s_nop 0
	v_rcp_f32_e32 v70, v70
	v_pk_add_f32 v[66:67], v[66:67], 1.0 op_sel_hi:[1,0]
	v_add_f32_e32 v69, v69, v77
	v_pk_mul_f32 v[70:71], v[70:71], v[86:87]
	v_lshlrev_b32_e32 v78, 16, v83
	v_cvt_pk_bf16_f32 v70, v70, v71
	v_add_f32_e32 v71, v72, v80
	v_mul_f32_e32 v71, 0xbfb8aa3b, v71
	v_exp_f32_e32 v72, v71
	v_add_f32_e32 v71, v73, v81
	v_mul_f32_e32 v71, 0xbfb8aa3b, v71
	v_exp_f32_e32 v73, v71
	v_and_b32_e32 v79, 0xffff0000, v83
	v_rcp_f32_e32 v67, v67
	v_mul_f32_e32 v69, 0xbfb8aa3b, v69
	v_pk_add_f32 v[72:73], v[72:73], 1.0 op_sel_hi:[1,0]
	v_exp_f32_e32 v69, v69
	s_nop 0
	v_rcp_f32_e32 v73, v73
	v_rcp_f32_e32 v72, v72
	s_nop 0
	v_pk_mul_f32 v[72:73], v[72:73], v[78:79]
	v_rcp_f32_e32 v66, v66
	v_cvt_pk_bf16_f32 v71, v72, v73
	v_lshlrev_b32_e32 v72, 16, v84
	v_and_b32_e32 v73, 0xffff0000, v84
	v_pk_mul_f32 v[66:67], v[66:67], v[72:73]
	v_add_u32_e32 v82, 0x80, v0
	v_cvt_pk_bf16_f32 v72, v66, v67
	v_add_f32_e32 v67, v68, v76
	v_mul_f32_e32 v67, 0xbfb8aa3b, v67
	v_exp_f32_e32 v68, v67
	v_lshlrev_b32_e32 v66, 16, v85
	v_and_b32_e32 v67, 0xffff0000, v85
	v_pk_add_f32 v[68:69], v[68:69], 1.0 op_sel_hi:[1,0]
	s_nop 0
	v_rcp_f32_e32 v69, v69
	v_rcp_f32_e32 v68, v68
	s_nop 0
	v_pk_mul_f32 v[66:67], v[68:69], v[66:67]
	s_nop 0
	v_cvt_pk_bf16_f32 v73, v66, v67
	global_store_dwordx4 v[106:107], v[70:73], off offset:256
	global_load_dwordx4 v[68:71], v[130:131], off offset:16
	s_nop 0
	global_load_dwordx4 v[72:75], v[130:131], off
	v_mad_i64_i32 v[66:67], s[0:1], v82, s81, v[134:135]
	v_lshl_add_u64 v[66:67], v[66:67], 0, v[132:133]
	global_load_dwordx4 v[76:79], v[66:67], off
	s_waitcnt vmcnt(0)
	v_add_f32_e32 v58, v58, v68
	v_add_f32_e32 v62, v62, v72
	v_add_f32_e32 v63, v63, v73
	v_mul_f32_e32 v62, 0xbfb8aa3b, v62
	v_mul_f32_e32 v63, 0xbfb8aa3b, v63
	v_exp_f32_e32 v62, v62
	v_exp_f32_e32 v63, v63
	v_lshlrev_b32_e32 v80, 16, v76
	v_and_b32_e32 v81, 0xffff0000, v76
	v_add_f32_e32 v59, v59, v69
	v_pk_add_f32 v[62:63], v[62:63], 1.0 op_sel_hi:[1,0]
	v_mul_f32_e32 v58, 0xbfb8aa3b, v58
	v_rcp_f32_e32 v63, v63
	v_mul_f32_e32 v59, 0xbfb8aa3b, v59
	v_exp_f32_e32 v58, v58
	v_exp_f32_e32 v59, v59
	s_nop 0
	v_rcp_f32_e32 v62, v62
	v_pk_add_f32 v[58:59], v[58:59], 1.0 op_sel_hi:[1,0]
	v_add_f32_e32 v61, v61, v71
	v_pk_mul_f32 v[62:63], v[62:63], v[80:81]
	v_lshlrev_b32_e32 v72, 16, v77
	v_cvt_pk_bf16_f32 v62, v62, v63
	v_add_f32_e32 v63, v64, v74
	v_mul_f32_e32 v63, 0xbfb8aa3b, v63
	v_exp_f32_e32 v64, v63
	v_add_f32_e32 v63, v65, v75
	v_mul_f32_e32 v63, 0xbfb8aa3b, v63
	v_exp_f32_e32 v65, v63
	v_and_b32_e32 v73, 0xffff0000, v77
	v_rcp_f32_e32 v59, v59
	v_mul_f32_e32 v61, 0xbfb8aa3b, v61
	v_pk_add_f32 v[64:65], v[64:65], 1.0 op_sel_hi:[1,0]
	v_exp_f32_e32 v61, v61
	s_nop 0
	v_rcp_f32_e32 v65, v65
	v_rcp_f32_e32 v64, v64
	s_nop 0
	v_pk_mul_f32 v[64:65], v[64:65], v[72:73]
	v_rcp_f32_e32 v58, v58
	v_cvt_pk_bf16_f32 v63, v64, v65
	v_lshlrev_b32_e32 v64, 16, v78
	v_and_b32_e32 v65, 0xffff0000, v78
	v_pk_mul_f32 v[58:59], v[58:59], v[64:65]
	v_add_u32_e32 v78, 0x90, v0
	v_cvt_pk_bf16_f32 v64, v58, v59
	v_add_f32_e32 v59, v60, v70
	v_mul_f32_e32 v59, 0xbfb8aa3b, v59
	v_exp_f32_e32 v60, v59
	v_lshlrev_b32_e32 v58, 16, v79
	v_and_b32_e32 v59, 0xffff0000, v79
	v_pk_add_f32 v[60:61], v[60:61], 1.0 op_sel_hi:[1,0]
	s_nop 0
	v_rcp_f32_e32 v61, v61
	v_rcp_f32_e32 v60, v60
	s_nop 0
	v_pk_mul_f32 v[58:59], v[60:61], v[58:59]
	s_nop 0
	v_cvt_pk_bf16_f32 v65, v58, v59
	v_mad_i64_i32 v[58:59], s[0:1], v82, s81, v[122:123]
	v_lshl_add_u64 v[60:61], v[58:59], 0, v[132:133]
	global_store_dwordx4 v[60:61], v[62:65], off
	global_load_dwordx4 v[62:65], v[130:131], off offset:16
	s_nop 0
	global_load_dwordx4 v[68:71], v[130:131], off
	v_mad_i64_i32 v[58:59], s[0:1], v78, s81, v[134:135]
	v_lshl_add_u64 v[58:59], v[58:59], 0, v[132:133]
	global_load_dwordx4 v[72:75], v[58:59], off
	s_waitcnt vmcnt(0)
	v_add_f32_e32 v50, v50, v62
	v_add_f32_e32 v54, v54, v68
	v_add_f32_e32 v55, v55, v69
	v_mul_f32_e32 v54, 0xbfb8aa3b, v54
	v_mul_f32_e32 v55, 0xbfb8aa3b, v55
	v_exp_f32_e32 v54, v54
	v_exp_f32_e32 v55, v55
	v_lshlrev_b32_e32 v76, 16, v72
	v_and_b32_e32 v77, 0xffff0000, v72
	v_add_f32_e32 v57, v57, v71
	v_pk_add_f32 v[54:55], v[54:55], 1.0 op_sel_hi:[1,0]
	v_mul_f32_e32 v57, 0xbfb8aa3b, v57
	v_rcp_f32_e32 v55, v55
	v_exp_f32_e32 v57, v57
	v_add_f32_e32 v51, v51, v63
	v_mul_f32_e32 v50, 0xbfb8aa3b, v50
	v_rcp_f32_e32 v54, v54
	v_mul_f32_e32 v51, 0xbfb8aa3b, v51
	v_exp_f32_e32 v50, v50
	v_exp_f32_e32 v51, v51
	s_nop 0
	v_pk_mul_f32 v[54:55], v[54:55], v[76:77]
	v_pk_add_f32 v[50:51], v[50:51], 1.0 op_sel_hi:[1,0]
	v_cvt_pk_bf16_f32 v68, v54, v55
	v_add_f32_e32 v55, v56, v70
	v_mul_f32_e32 v55, 0xbfb8aa3b, v55
	v_exp_f32_e32 v56, v55
	v_lshlrev_b32_e32 v54, 16, v73
	v_and_b32_e32 v55, 0xffff0000, v73
	v_add_f32_e32 v53, v53, v65
	v_pk_add_f32 v[56:57], v[56:57], 1.0 op_sel_hi:[1,0]
	v_mul_f32_e32 v53, 0xbfb8aa3b, v53
	v_rcp_f32_e32 v57, v57
	v_exp_f32_e32 v53, v53
	s_nop 0
	v_rcp_f32_e32 v56, v56
	s_nop 0
	v_pk_mul_f32 v[54:55], v[56:57], v[54:55]
	v_rcp_f32_e32 v51, v51
	v_cvt_pk_bf16_f32 v69, v54, v55
	v_lshlrev_b32_e32 v54, 16, v74
	v_and_b32_e32 v55, 0xffff0000, v74
	v_rcp_f32_e32 v50, v50
	s_nop 0
	v_pk_mul_f32 v[50:51], v[50:51], v[54:55]
	s_nop 0
	v_cvt_pk_bf16_f32 v70, v50, v51
	v_add_f32_e32 v51, v52, v64
	v_mul_f32_e32 v51, 0xbfb8aa3b, v51
	v_exp_f32_e32 v52, v51
	v_lshlrev_b32_e32 v50, 16, v75
	v_and_b32_e32 v51, 0xffff0000, v75
	v_pk_add_f32 v[52:53], v[52:53], 1.0 op_sel_hi:[1,0]
	s_nop 0
	v_rcp_f32_e32 v53, v53
	v_rcp_f32_e32 v52, v52
	s_nop 0
	v_pk_mul_f32 v[50:51], v[52:53], v[50:51]
	v_add_u32_e32 v56, 0xa0, v0
	v_cvt_pk_bf16_f32 v71, v50, v51
	v_mad_i64_i32 v[50:51], s[0:1], v78, s81, v[122:123]
	v_lshl_add_u64 v[54:55], v[50:51], 0, v[132:133]
	global_store_dwordx4 v[54:55], v[68:71], off
	global_load_dwordx4 v[62:65], v[130:131], off offset:16
	s_nop 0
	global_load_dwordx4 v[68:71], v[130:131], off
	v_mad_i64_i32 v[50:51], s[0:1], v56, s81, v[134:135]
	v_lshl_add_u64 v[52:53], v[50:51], 0, v[132:133]
	global_load_dwordx4 v[72:75], v[52:53], off
	v_add_u32_e32 v0, 0xb0, v0
	s_waitcnt vmcnt(0)
; DI unsigned pack2(float a, float b) { f32x2_t v = {a, b}; bf16x2_t r = __builtin_convertvector(v, bf16x2_t); return __builtin_bit_cast(unsigned, r); }
; DI float lo16(unsigned u) { return __uint_as_float(u << 16); }
; DI float hi16(unsigned u) { return __uint_as_float(u & 0xffff0000u); }
; DI float sigmoidf_(float x) { return 1.f / (1.f + __expf(-x)); }
; DI bfu* wsb(const PX& p, size_t off) { return (bfu*)(p.ws + off); }
; template <int EPI, int HM>
; DI void epi256(const PX& p, int l, f32x4 (&acc)[2][2][4][2], int brow, int bcol, int aux, bool src_input) {
;     ...
;           } else if (EPI == EPI_GLU) {
;             const float* gbp = p.in[30] + l * 768 + col0;
;             const f32x4 g0 = *(const f32x4*)gbp, g1 = *(const f32x4*)(gbp + 4);
;             const float gb[8] = {g0[0], g0[1], g0[2], g0[3], g1[0], g1[1], g1[2], g1[3]};
;             const uint4 z = *(const uint4*)(wsb(p, OFF_BIG + B_YF) + (size_t)row * 768 + col0);
;             const unsigned zz[4] = {z.x, z.y, z.z, z.w};
;             unsigned oo[4];
; #pragma unroll
;             for (int q = 0; q < 4; q++)
;               oo[q] = pack2(lo16(zz[q]) * sigmoidf_(v[2 * q] + gb[2 * q]), hi16(zz[q]) * sigmoidf_(v[2 * q + 1] + gb[2 * q + 1]));
;             *(uint4*)(wsb(p, OFF_BIG + B_YB) + (size_t)row * 768 + col0) = make_uint4(oo[0], oo[1], oo[2], oo[3]);
	v_add_f32_e32 v42, v42, v62
	v_add_f32_e32 v46, v46, v68
	v_add_f32_e32 v47, v47, v69
	v_mul_f32_e32 v46, 0xbfb8aa3b, v46
	v_mul_f32_e32 v47, 0xbfb8aa3b, v47
	v_exp_f32_e32 v46, v46
	v_exp_f32_e32 v47, v47
	v_lshlrev_b32_e32 v50, 16, v72
	v_and_b32_e32 v51, 0xffff0000, v72
	v_add_f32_e32 v43, v43, v63
	v_pk_add_f32 v[46:47], v[46:47], 1.0 op_sel_hi:[1,0]
	v_mul_f32_e32 v42, 0xbfb8aa3b, v42
	v_rcp_f32_e32 v47, v47
	v_mul_f32_e32 v43, 0xbfb8aa3b, v43
	v_exp_f32_e32 v42, v42
	v_exp_f32_e32 v43, v43
	s_nop 0
	v_rcp_f32_e32 v46, v46
	v_pk_add_f32 v[42:43], v[42:43], 1.0 op_sel_hi:[1,0]
	v_add_f32_e32 v45, v45, v65
	v_mul_f32_e32 v45, 0xbfb8aa3b, v45
	v_pk_mul_f32 v[46:47], v[46:47], v[50:51]
	v_lshlrev_b32_e32 v50, 16, v73
	v_cvt_pk_bf16_f32 v46, v46, v47
	v_add_f32_e32 v47, v48, v70
	v_mul_f32_e32 v47, 0xbfb8aa3b, v47
	v_exp_f32_e32 v48, v47
	v_add_f32_e32 v47, v49, v71
	v_mul_f32_e32 v47, 0xbfb8aa3b, v47
	v_exp_f32_e32 v49, v47
	v_and_b32_e32 v51, 0xffff0000, v73
	v_exp_f32_e32 v45, v45
	v_pk_add_f32 v[48:49], v[48:49], 1.0 op_sel_hi:[1,0]
	s_nop 0
	v_rcp_f32_e32 v49, v49
	v_rcp_f32_e32 v48, v48
	s_nop 0
	v_pk_mul_f32 v[48:49], v[48:49], v[50:51]
	v_rcp_f32_e32 v43, v43
	v_cvt_pk_bf16_f32 v47, v48, v49
	v_lshlrev_b32_e32 v48, 16, v74
	v_and_b32_e32 v49, 0xffff0000, v74
	v_rcp_f32_e32 v42, v42
	s_nop 0
	v_pk_mul_f32 v[42:43], v[42:43], v[48:49]
	s_nop 0
	v_cvt_pk_bf16_f32 v48, v42, v43
	v_add_f32_e32 v43, v44, v64
	v_mul_f32_e32 v43, 0xbfb8aa3b, v43
	v_exp_f32_e32 v44, v43
	v_lshlrev_b32_e32 v42, 16, v75
	v_and_b32_e32 v43, 0xffff0000, v75
	v_pk_add_f32 v[44:45], v[44:45], 1.0 op_sel_hi:[1,0]
	s_nop 0
	v_rcp_f32_e32 v45, v45
	v_rcp_f32_e32 v44, v44
	s_nop 0
	v_pk_mul_f32 v[42:43], v[44:45], v[42:43]
	s_nop 0
	v_cvt_pk_bf16_f32 v49, v42, v43
	v_mad_i64_i32 v[42:43], s[0:1], v56, s81, v[122:123]
	v_lshl_add_u64 v[50:51], v[42:43], 0, v[132:133]
	global_store_dwordx4 v[50:51], v[46:49], off
	global_load_dwordx4 v[42:45], v[130:131], off offset:16
	global_load_dwordx4 v[62:65], v[130:131], off
	v_mad_i64_i32 v[46:47], s[0:1], v0, s81, v[134:135]
	v_lshl_add_u64 v[48:49], v[46:47], 0, v[132:133]
	global_load_dwordx4 v[68:71], v[48:49], off
	s_waitcnt vmcnt(0)
	v_add_f32_e32 v34, v34, v42
	v_add_f32_e32 v38, v38, v62
	v_add_f32_e32 v39, v39, v63
	v_mul_f32_e32 v38, 0xbfb8aa3b, v38
	v_mul_f32_e32 v39, 0xbfb8aa3b, v39
	v_exp_f32_e32 v38, v38
	v_exp_f32_e32 v39, v39
	v_lshlrev_b32_e32 v46, 16, v68
	v_and_b32_e32 v47, 0xffff0000, v68
	v_add_f32_e32 v35, v35, v43
	v_pk_add_f32 v[38:39], v[38:39], 1.0 op_sel_hi:[1,0]
	v_mul_f32_e32 v34, 0xbfb8aa3b, v34
	v_rcp_f32_e32 v39, v39
	v_mul_f32_e32 v35, 0xbfb8aa3b, v35
	v_exp_f32_e32 v34, v34
	v_exp_f32_e32 v35, v35
	s_nop 0
	v_rcp_f32_e32 v38, v38
	v_pk_add_f32 v[34:35], v[34:35], 1.0 op_sel_hi:[1,0]
	v_add_f32_e32 v37, v37, v45
	v_pk_mul_f32 v[38:39], v[38:39], v[46:47]
	v_rcp_f32_e32 v35, v35
	v_cvt_pk_bf16_f32 v38, v38, v39
	v_add_f32_e32 v39, v40, v64
	v_mul_f32_e32 v39, 0xbfb8aa3b, v39
	v_exp_f32_e32 v40, v39
	v_add_f32_e32 v39, v41, v65
	v_mul_f32_e32 v39, 0xbfb8aa3b, v39
	v_exp_f32_e32 v41, v39
	v_lshlrev_b32_e32 v46, 16, v69
	v_and_b32_e32 v47, 0xffff0000, v69
	v_mul_f32_e32 v37, 0xbfb8aa3b, v37
	v_pk_add_f32 v[40:41], v[40:41], 1.0 op_sel_hi:[1,0]
	v_exp_f32_e32 v37, v37
	s_nop 0
	v_rcp_f32_e32 v41, v41
	v_rcp_f32_e32 v40, v40
	s_nop 0
	v_pk_mul_f32 v[40:41], v[40:41], v[46:47]
	v_rcp_f32_e32 v34, v34
	v_cvt_pk_bf16_f32 v39, v40, v41
	v_lshlrev_b32_e32 v40, 16, v70
	v_and_b32_e32 v41, 0xffff0000, v70
	v_pk_mul_f32 v[34:35], v[34:35], v[40:41]
	s_nop 0
	v_cvt_pk_bf16_f32 v40, v34, v35
	v_add_f32_e32 v35, v36, v44
	v_mul_f32_e32 v35, 0xbfb8aa3b, v35
	v_exp_f32_e32 v36, v35
	v_lshlrev_b32_e32 v34, 16, v71
	v_and_b32_e32 v35, 0xffff0000, v71
	v_pk_add_f32 v[36:37], v[36:37], 1.0 op_sel_hi:[1,0]
	s_nop 0
	v_rcp_f32_e32 v37, v37
	v_rcp_f32_e32 v36, v36
	s_nop 0
	v_pk_mul_f32 v[34:35], v[36:37], v[34:35]
	s_nop 0
	v_cvt_pk_bf16_f32 v41, v34, v35
	v_mad_i64_i32 v[34:35], s[0:1], v0, s81, v[122:123]
	v_lshl_add_u64 v[46:47], v[34:35], 0, v[132:133]
	global_store_dwordx4 v[46:47], v[38:41], off
	global_load_dwordx4 v[34:37], v[130:131], off offset:528
	s_nop 0
	global_load_dwordx4 v[38:41], v[130:131], off offset:512
	global_load_dwordx4 v[42:45], v[66:67], off offset:256
	s_waitcnt vmcnt(0)
	v_add_f32_e32 v0, v30, v38
	v_mul_f32_e32 v0, 0xbfb8aa3b, v0
	v_exp_f32_e32 v30, v0
	v_add_f32_e32 v0, v31, v39
	v_mul_f32_e32 v0, 0xbfb8aa3b, v0
	v_exp_f32_e32 v31, v0
	v_lshlrev_b32_e32 v56, 16, v42
	v_and_b32_e32 v57, 0xffff0000, v42
	v_pk_add_f32 v[30:31], v[30:31], 1.0 op_sel_hi:[1,0]
	s_nop 0
	v_rcp_f32_e32 v31, v31
	v_rcp_f32_e32 v30, v30
	s_nop 0
	v_add_f32_e32 v0, v32, v40
	v_mul_f32_e32 v0, 0xbfb8aa3b, v0
	v_exp_f32_e32 v32, v0
	v_add_f32_e32 v0, v33, v41
	v_mul_f32_e32 v0, 0xbfb8aa3b, v0
	v_exp_f32_e32 v33, v0
	v_pk_mul_f32 v[30:31], v[30:31], v[56:57]
	v_lshlrev_b32_e32 v38, 16, v43
	v_cvt_pk_bf16_f32 v30, v30, v31
	v_pk_add_f32 v[32:33], v[32:33], 1.0 op_sel_hi:[1,0]
	v_and_b32_e32 v39, 0xffff0000, v43
	v_rcp_f32_e32 v33, v33
	v_rcp_f32_e32 v32, v32
	s_nop 0
	v_add_f32_e32 v0, v26, v34
	v_mul_f32_e32 v0, 0xbfb8aa3b, v0
	v_exp_f32_e32 v26, v0
	v_add_f32_e32 v0, v27, v35
	v_mul_f32_e32 v0, 0xbfb8aa3b, v0
	v_exp_f32_e32 v27, v0
	v_pk_mul_f32 v[32:33], v[32:33], v[38:39]
	v_pk_add_f32 v[26:27], v[26:27], 1.0 op_sel_hi:[1,0]
	s_nop 0
	v_rcp_f32_e32 v27, v27
	v_cvt_pk_bf16_f32 v31, v32, v33
	v_lshlrev_b32_e32 v32, 16, v44
	v_and_b32_e32 v33, 0xffff0000, v44
	v_rcp_f32_e32 v26, v26
	s_nop 0
	v_add_f32_e32 v0, v28, v36
	v_mul_f32_e32 v0, 0xbfb8aa3b, v0
	v_exp_f32_e32 v28, v0
	v_add_f32_e32 v0, v29, v37
	v_mul_f32_e32 v0, 0xbfb8aa3b, v0
	v_exp_f32_e32 v29, v0
	v_pk_mul_f32 v[26:27], v[26:27], v[32:33]
	v_pk_add_f32 v[28:29], v[28:29], 1.0 op_sel_hi:[1,0]
	s_nop 0
	v_rcp_f32_e32 v29, v29
	v_cvt_pk_bf16_f32 v32, v26, v27
	v_lshlrev_b32_e32 v26, 16, v45
	v_and_b32_e32 v27, 0xffff0000, v45
	v_rcp_f32_e32 v28, v28
	s_nop 0
	v_pk_mul_f32 v[26:27], v[28:29], v[26:27]
	s_nop 0
	v_cvt_pk_bf16_f32 v33, v26, v27
	global_store_dwordx4 v[60:61], v[30:33], off offset:256
	global_load_dwordx4 v[26:29], v[130:131], off offset:528
	global_load_dwordx4 v[34:37], v[130:131], off offset:512
	s_nop 0
	global_load_dwordx4 v[30:33], v[58:59], off offset:256
	s_waitcnt vmcnt(0)
; DI unsigned pack2(float a, float b) { f32x2_t v = {a, b}; bf16x2_t r = __builtin_convertvector(v, bf16x2_t); return __builtin_bit_cast(unsigned, r); }
; DI float lo16(unsigned u) { return __uint_as_float(u << 16); }
; DI float hi16(unsigned u) { return __uint_as_float(u & 0xffff0000u); }
; DI float sigmoidf_(float x) { return 1.f / (1.f + __expf(-x)); }
; DI bfu* wsb(const PX& p, size_t off) { return (bfu*)(p.ws + off); }
; template <int EPI, int HM>
; DI void epi256(const PX& p, int l, f32x4 (&acc)[2][2][4][2], int brow, int bcol, int aux, bool src_input) {
;     ...
;           } else if (EPI == EPI_GLU) {
;             const float* gbp = p.in[30] + l * 768 + col0;
;             const f32x4 g0 = *(const f32x4*)gbp, g1 = *(const f32x4*)(gbp + 4);
;             const float gb[8] = {g0[0], g0[1], g0[2], g0[3], g1[0], g1[1], g1[2], g1[3]};
;             const uint4 z = *(const uint4*)(wsb(p, OFF_BIG + B_YF) + (size_t)row * 768 + col0);
;             const unsigned zz[4] = {z.x, z.y, z.z, z.w};
;             unsigned oo[4];
; #pragma unroll
;             for (int q = 0; q < 4; q++)
;               oo[q] = pack2(lo16(zz[q]) * sigmoidf_(v[2 * q] + gb[2 * q]), hi16(zz[q]) * sigmoidf_(v[2 * q + 1] + gb[2 * q + 1]));
;             *(uint4*)(wsb(p, OFF_BIG + B_YB) + (size_t)row * 768 + col0) = make_uint4(oo[0], oo[1], oo[2], oo[3]);
	v_add_f32_e32 v0, v22, v34
	v_mul_f32_e32 v0, 0xbfb8aa3b, v0
	v_exp_f32_e32 v22, v0
	v_add_f32_e32 v0, v23, v35
	v_mul_f32_e32 v0, 0xbfb8aa3b, v0
	v_exp_f32_e32 v23, v0
	v_lshlrev_b32_e32 v38, 16, v30
	v_and_b32_e32 v39, 0xffff0000, v30
	v_pk_add_f32 v[22:23], v[22:23], 1.0 op_sel_hi:[1,0]
	s_nop 0
	v_rcp_f32_e32 v23, v23
	v_rcp_f32_e32 v22, v22
	s_nop 0
	v_add_f32_e32 v0, v24, v36
	v_mul_f32_e32 v0, 0xbfb8aa3b, v0
	v_exp_f32_e32 v24, v0
	v_add_f32_e32 v0, v25, v37
	v_mul_f32_e32 v0, 0xbfb8aa3b, v0
	v_exp_f32_e32 v25, v0
	v_pk_mul_f32 v[22:23], v[22:23], v[38:39]
	v_lshlrev_b32_e32 v30, 16, v31
	v_cvt_pk_bf16_f32 v22, v22, v23
	v_pk_add_f32 v[24:25], v[24:25], 1.0 op_sel_hi:[1,0]
	v_and_b32_e32 v31, 0xffff0000, v31
	v_rcp_f32_e32 v25, v25
	v_rcp_f32_e32 v24, v24
	s_nop 0
	v_add_f32_e32 v0, v18, v26
	v_mul_f32_e32 v0, 0xbfb8aa3b, v0
	v_exp_f32_e32 v18, v0
	v_add_f32_e32 v0, v19, v27
	v_mul_f32_e32 v0, 0xbfb8aa3b, v0
	v_exp_f32_e32 v19, v0
	v_pk_mul_f32 v[24:25], v[24:25], v[30:31]
	v_pk_add_f32 v[18:19], v[18:19], 1.0 op_sel_hi:[1,0]
	s_nop 0
	v_rcp_f32_e32 v19, v19
	v_cvt_pk_bf16_f32 v23, v24, v25
	v_lshlrev_b32_e32 v24, 16, v32
	v_and_b32_e32 v25, 0xffff0000, v32
	v_rcp_f32_e32 v18, v18
	s_nop 0
	v_add_f32_e32 v0, v20, v28
	v_mul_f32_e32 v0, 0xbfb8aa3b, v0
	v_exp_f32_e32 v20, v0
	v_add_f32_e32 v0, v21, v29
	v_mul_f32_e32 v0, 0xbfb8aa3b, v0
	v_exp_f32_e32 v21, v0
	v_pk_mul_f32 v[18:19], v[18:19], v[24:25]
	v_pk_add_f32 v[20:21], v[20:21], 1.0 op_sel_hi:[1,0]
	s_nop 0
	v_rcp_f32_e32 v21, v21
	v_cvt_pk_bf16_f32 v24, v18, v19
	v_lshlrev_b32_e32 v18, 16, v33
	v_and_b32_e32 v19, 0xffff0000, v33
	v_rcp_f32_e32 v20, v20
	s_nop 0
	v_pk_mul_f32 v[18:19], v[20:21], v[18:19]
	s_nop 0
	v_cvt_pk_bf16_f32 v25, v18, v19
	global_store_dwordx4 v[54:55], v[22:25], off offset:256
	global_load_dwordx4 v[18:21], v[130:131], off offset:528
	global_load_dwordx4 v[26:29], v[130:131], off offset:512
	s_nop 0
	global_load_dwordx4 v[22:25], v[52:53], off offset:256
	s_waitcnt vmcnt(0)
	v_add_f32_e32 v0, v14, v26
	v_mul_f32_e32 v0, 0xbfb8aa3b, v0
	v_exp_f32_e32 v14, v0
	v_add_f32_e32 v0, v15, v27
	v_mul_f32_e32 v0, 0xbfb8aa3b, v0
	v_exp_f32_e32 v15, v0
	v_lshlrev_b32_e32 v30, 16, v22
	v_and_b32_e32 v31, 0xffff0000, v22
	v_pk_add_f32 v[14:15], v[14:15], 1.0 op_sel_hi:[1,0]
	s_nop 0
	v_rcp_f32_e32 v15, v15
	v_rcp_f32_e32 v14, v14
	s_nop 0
	v_add_f32_e32 v0, v16, v28
	v_mul_f32_e32 v0, 0xbfb8aa3b, v0
	v_exp_f32_e32 v16, v0
	v_add_f32_e32 v0, v17, v29
	v_mul_f32_e32 v0, 0xbfb8aa3b, v0
	v_exp_f32_e32 v17, v0
	v_pk_mul_f32 v[14:15], v[14:15], v[30:31]
	v_lshlrev_b32_e32 v22, 16, v23
	v_cvt_pk_bf16_f32 v14, v14, v15
	v_pk_add_f32 v[16:17], v[16:17], 1.0 op_sel_hi:[1,0]
	v_and_b32_e32 v23, 0xffff0000, v23
	v_rcp_f32_e32 v17, v17
	v_rcp_f32_e32 v16, v16
	s_nop 0
	v_add_f32_e32 v0, v10, v18
	v_mul_f32_e32 v0, 0xbfb8aa3b, v0
	v_exp_f32_e32 v10, v0
	v_add_f32_e32 v0, v11, v19
	v_mul_f32_e32 v0, 0xbfb8aa3b, v0
	v_exp_f32_e32 v11, v0
	v_pk_mul_f32 v[16:17], v[16:17], v[22:23]
	v_pk_add_f32 v[10:11], v[10:11], 1.0 op_sel_hi:[1,0]
	s_nop 0
	v_rcp_f32_e32 v11, v11
	v_cvt_pk_bf16_f32 v15, v16, v17
	v_lshlrev_b32_e32 v16, 16, v24
	v_and_b32_e32 v17, 0xffff0000, v24
	v_rcp_f32_e32 v10, v10
	s_nop 0
	v_add_f32_e32 v0, v12, v20
	v_mul_f32_e32 v0, 0xbfb8aa3b, v0
	v_exp_f32_e32 v12, v0
	v_add_f32_e32 v0, v13, v21
	v_mul_f32_e32 v0, 0xbfb8aa3b, v0
	v_exp_f32_e32 v13, v0
	v_pk_mul_f32 v[10:11], v[10:11], v[16:17]
	v_pk_add_f32 v[12:13], v[12:13], 1.0 op_sel_hi:[1,0]
	s_nop 0
	v_rcp_f32_e32 v13, v13
	v_cvt_pk_bf16_f32 v16, v10, v11
	v_lshlrev_b32_e32 v10, 16, v25
	v_and_b32_e32 v11, 0xffff0000, v25
	v_rcp_f32_e32 v12, v12
	s_nop 0
	v_pk_mul_f32 v[10:11], v[12:13], v[10:11]
	s_nop 0
	v_cvt_pk_bf16_f32 v17, v10, v11
	global_store_dwordx4 v[50:51], v[14:17], off offset:256
	global_load_dwordx4 v[10:13], v[130:131], off offset:528
	global_load_dwordx4 v[18:21], v[130:131], off offset:512
	s_nop 0
	global_load_dwordx4 v[14:17], v[48:49], off offset:256
	s_waitcnt vmcnt(0)
	v_add_f32_e32 v0, v6, v18
	v_mul_f32_e32 v0, 0xbfb8aa3b, v0
	v_exp_f32_e32 v6, v0
	v_add_f32_e32 v0, v7, v19
	v_mul_f32_e32 v0, 0xbfb8aa3b, v0
	v_exp_f32_e32 v7, v0
	v_lshlrev_b32_e32 v22, 16, v14
	v_and_b32_e32 v23, 0xffff0000, v14
	v_pk_add_f32 v[6:7], v[6:7], 1.0 op_sel_hi:[1,0]
	s_nop 0
	v_rcp_f32_e32 v7, v7
	v_rcp_f32_e32 v6, v6
	s_nop 0
	v_add_f32_e32 v0, v8, v20
	v_mul_f32_e32 v0, 0xbfb8aa3b, v0
	v_exp_f32_e32 v8, v0
	v_add_f32_e32 v0, v9, v21
	v_mul_f32_e32 v0, 0xbfb8aa3b, v0
	v_exp_f32_e32 v9, v0
	v_pk_mul_f32 v[6:7], v[6:7], v[22:23]
	v_lshlrev_b32_e32 v14, 16, v15
	v_cvt_pk_bf16_f32 v6, v6, v7
	v_pk_add_f32 v[8:9], v[8:9], 1.0 op_sel_hi:[1,0]
	v_and_b32_e32 v15, 0xffff0000, v15
	v_rcp_f32_e32 v9, v9
	v_rcp_f32_e32 v8, v8
	s_nop 0
	v_add_f32_e32 v0, v2, v10
	v_mul_f32_e32 v0, 0xbfb8aa3b, v0
	v_exp_f32_e32 v2, v0
	v_add_f32_e32 v0, v3, v11
	v_mul_f32_e32 v0, 0xbfb8aa3b, v0
	v_exp_f32_e32 v3, v0
	v_pk_mul_f32 v[8:9], v[8:9], v[14:15]
	v_pk_add_f32 v[2:3], v[2:3], 1.0 op_sel_hi:[1,0]
	s_nop 0
	v_rcp_f32_e32 v3, v3
	v_cvt_pk_bf16_f32 v7, v8, v9
	v_lshlrev_b32_e32 v8, 16, v16
	v_and_b32_e32 v9, 0xffff0000, v16
	v_rcp_f32_e32 v2, v2
	s_nop 0
	v_add_f32_e32 v0, v4, v12
	v_mul_f32_e32 v0, 0xbfb8aa3b, v0
	v_exp_f32_e32 v4, v0
	v_add_f32_e32 v0, v5, v13
	v_mul_f32_e32 v0, 0xbfb8aa3b, v0
	v_exp_f32_e32 v5, v0
	v_pk_mul_f32 v[2:3], v[2:3], v[8:9]
	v_pk_add_f32 v[4:5], v[4:5], 1.0 op_sel_hi:[1,0]
	s_nop 0
	v_rcp_f32_e32 v5, v5
	v_cvt_pk_bf16_f32 v8, v2, v3
	v_lshlrev_b32_e32 v2, 16, v17
	v_and_b32_e32 v3, 0xffff0000, v17
	v_rcp_f32_e32 v4, v4
	s_mov_b32 s0, s61
	s_mov_b32 s1, s60
	v_pk_mul_f32 v[2:3], v[4:5], v[2:3]
	s_and_b64 vcc, exec, s[8:9]
	v_cvt_pk_bf16_f32 v9, v2, v3
	global_store_dwordx4 v[46:47], v[6:9], off offset:256
	s_cbranch_vccnz .LBB0_363

; DI void s5_job(const PX& p, int l, int job, unsigned char* smem) {
;     ...
;   for (int seg = 0; seg < 2; seg++) {
;     const int Lseg = seg ? 2048 : 256;
;     const int tokbase = seg ? b * 2048 : NLAT + b * 256;
;     const int nblk = Lseg >> 3;
;     uint4 ucur[8], unext[8];
;     if (active) {
; #pragma unroll
;       for (int s = 0; s < 8; s++) {
;         const int t = dir ? Lseg - 1 - s : s;
;         ucur[s] = *(const uint4*)(Zu + (size_t)(tokbase + t) * 768);
;       }
;     }
; #pragma unroll 1
;     for (int blk = 0; blk < nblk; blk++, gblk++) {
;       float* exb = ex + (gblk & 1) * (32 * 64) + lane;
;       f32x4 yp[8];
;       if (active) {
;         if (blk + 1 < nblk) {
; #pragma unroll
;           for (int s = 0; s < 8; s++) {
;             const int st = (blk + 1) * 8 + s;
;             const int t = dir ? Lseg - 1 - st : st;
;             unext[s] = *(const uint4*)(Zu + (size_t)(tokbase + t) * 768);
;           }
.LBB0_499:
	s_waitcnt vmcnt(0)
	s_add_i32 s0, s0, s18
	s_mov_b64 s[14:15], 0
	s_and_b64 vcc, exec, s[12:13]
	s_cbranch_vccnz .LBB0_425
.LBB0_500:
	s_and_b64 s[2:3], s[14:15], exec
	s_movk_i32 s1, 0x800
	s_cselect_b32 s1, 0x100, s1
	v_cndmask_b32_e64 v2, v160, v161, s[14:15]
	s_and_saveexec_b64 s[12:13], s[4:5]
	s_cbranch_execz .LBB0_502
	s_add_i32 s2, s1, -1
	v_mov_b32_e32 v0, s2
	v_cndmask_b32_e64 v0, v0, 0, s[6:7]
	v_add_u32_e32 v0, v0, v2
	v_mul_i32_i24_e32 v0, 0x300, v0
	s_add_i32 s2, s1, -2
	s_waitcnt vmcnt(6)
	v_lshl_add_u64 v[36:37], v[0:1], 1, v[156:157]
	v_mov_b32_e32 v0, s2
	v_cndmask_b32_e64 v0, v0, 1, s[6:7]
	v_add_u32_e32 v0, v0, v2
	v_mul_i32_i24_e32 v0, 0x300, v0
	s_add_i32 s2, s1, -3
	v_lshl_add_u64 v[38:39], v[0:1], 1, v[156:157]
	v_mov_b32_e32 v0, s2
	v_cndmask_b32_e64 v0, v0, 2, s[6:7]
	v_add_u32_e32 v0, v0, v2
	v_mul_i32_i24_e32 v0, 0x300, v0
	s_add_i32 s2, s1, -4
	s_waitcnt vmcnt(4)
	v_lshl_add_u64 v[52:53], v[0:1], 1, v[156:157]
	v_mov_b32_e32 v0, s2
	v_cndmask_b32_e64 v0, v0, 3, s[6:7]
	v_add_u32_e32 v0, v0, v2
	v_mul_i32_i24_e32 v0, 0x300, v0
	s_add_i32 s2, s1, -5
	v_lshl_add_u64 v[54:55], v[0:1], 1, v[156:157]
	v_mov_b32_e32 v0, s2
	v_cndmask_b32_e64 v0, v0, 4, s[6:7]
	v_add_u32_e32 v0, v0, v2
	v_mul_i32_i24_e32 v0, 0x300, v0
	s_add_i32 s2, s1, -6
	s_waitcnt vmcnt(2)
	v_lshl_add_u64 v[68:69], v[0:1], 1, v[156:157]
	v_mov_b32_e32 v0, s2
	v_cndmask_b32_e64 v0, v0, 5, s[6:7]
	v_add_u32_e32 v0, v0, v2
	v_mul_i32_i24_e32 v0, 0x300, v0
	s_add_i32 s2, s1, -7
	v_lshl_add_u64 v[70:71], v[0:1], 1, v[156:157]
	v_mov_b32_e32 v0, s2
	v_cndmask_b32_e64 v0, v0, 6, s[6:7]
	v_add_u32_e32 v0, v0, v2
	v_mul_i32_i24_e32 v0, 0x300, v0
	s_add_i32 s2, s1, -8
	s_waitcnt vmcnt(0)
	v_lshl_add_u64 v[84:85], v[0:1], 1, v[156:157]
	v_mov_b32_e32 v0, s2
	v_cndmask_b32_e64 v0, v0, 7, s[6:7]
	v_add_u32_e32 v0, v0, v2
	v_mul_i32_i24_e32 v0, 0x300, v0
	v_lshl_add_u64 v[86:87], v[0:1], 1, v[156:157]
	global_load_dwordx4 v[40:43], v[36:37], off
	s_nop 0
	global_load_dwordx4 v[36:39], v[38:39], off
	s_nop 0
	global_load_dwordx4 v[56:59], v[52:53], off
	s_nop 0
	global_load_dwordx4 v[52:55], v[54:55], off
	s_nop 0
	global_load_dwordx4 v[72:75], v[68:69], off
	s_nop 0
	global_load_dwordx4 v[68:71], v[70:71], off
	s_nop 0
	global_load_dwordx4 v[88:91], v[84:85], off
	s_nop 0
	global_load_dwordx4 v[84:87], v[86:87], off
	s_add_i32 s16, s1, -9
	v_mov_b32_e32 v208, s16
	v_cndmask_b32_e64 v208, v208, 8, s[6:7]
	v_add_u32_e32 v208, v208, v2
	v_mad_i64_i32 v[190:191], s[16:17], v208, s81, v[156:157]
	v_mov_b32_e32 v208, 0x600
	v_mov_b32_e32 v209, 0xfffffa00
	v_cndmask_b32_e64 v208, v209, v208, s[6:7]
	v_cndmask_b32_e64 v209, -1, 0, s[6:7]
	v_lshlrev_b64 v[206:207], 3, v[208:209]
	v_lshl_add_u64 v[192:193], v[190:191], 0, v[208:209]
	v_lshl_add_u64 v[194:195], v[192:193], 0, v[208:209]
	v_lshl_add_u64 v[196:197], v[194:195], 0, v[208:209]
	v_lshl_add_u64 v[198:199], v[196:197], 0, v[208:209]
	v_lshl_add_u64 v[200:201], v[198:199], 0, v[208:209]
	v_lshl_add_u64 v[202:203], v[200:201], 0, v[208:209]
	v_lshl_add_u64 v[204:205], v[202:203], 0, v[208:209]
	s_waitcnt vmcnt(0)

; DI unsigned pack2(float a, float b) { f32x2_t v = {a, b}; bf16x2_t r = __builtin_convertvector(v, bf16x2_t); return __builtin_bit_cast(unsigned, r); }
; DI f32x4 mfma16(bf16x8 a, bf16x8 b, f32x4 c) { return __builtin_amdgcn_mfma_f32_16x16x32_bf16(a, b, c, 0, 0, 0); }
; DI void s5_job(const PX& p, int l, int job, unsigned char* smem) {
;     ...
;           for (int s = 0; s < 8; s++) {
;             const int st = (blk + 1) * 8 + s;
;             const int t = dir ? Lseg - 1 - st : st;
;             unext[s] = *(const uint4*)(Zu + (size_t)(tokbase + t) * 768);
;           }
;         }
; #pragma unroll
;         for (int s = 0; s < 8; s++) {
;           const bf16x8 ub = u4_to_bf8(ucur[s]);
; #pragma unroll
;           for (int tt = 0; tt < 2; tt++) {
;             f32x4 cr, ci;
; #pragma unroll
;             for (int r = 0; r < 4; r++) {
;               cr[r] = lre[tt][r] * sre[tt][r] - lim[tt][r] * sim[tt][r];
;               ci[r] = lre[tt][r] * sim[tt][r] + lim[tt][r] * sre[tt][r];
;             }
;             sre[tt] = mfma16(Are[tt], ub, cr);
;             sim[tt] = mfma16(Aim[tt], ub, ci);
;           }
;           uint4 pr, pi;
;           pr.x = pack2(sre[0][0], sre[0][1]); pr.y = pack2(sre[0][2], sre[0][3]);
;           pr.z = pack2(sre[1][0], sre[1][1]); pr.w = pack2(sre[1][2], sre[1][3]);
;           pi.x = pack2(sim[0][0], sim[0][1]); pi.y = pack2(sim[0][2], sim[0][3]);
;           pi.z = pack2(sim[1][0], sim[1][1]); pi.w = pack2(sim[1][2], sim[1][3]);
;           f32x4 y = f32x4{0.f, 0.f, 0.f, 0.f};
;           y = mfma16(Cf[0], u4_to_bf8(pr), y);
;           y = mfma16(Cf[1], u4_to_bf8(pi), y);
;           yp[s] = y;
;         }
.LBB0_507:
	v_pk_mul_f32 v[92:93], v[146:147], v[122:123]
	v_pk_mul_f32 v[96:97], v[142:143], v[120:121]
	v_pk_fma_f32 v[94:95], v[144:145], v[118:119], v[92:93] neg_lo:[0,0,1] neg_hi:[0,0,1]
	v_pk_fma_f32 v[92:93], v[140:141], v[116:117], v[96:97] neg_lo:[0,0,1] neg_hi:[0,0,1]
	v_pk_mul_f32 v[100:101], v[144:145], v[122:123]
	v_pk_mul_f32 v[104:105], v[150:151], v[112:113]
	s_waitcnt vmcnt(11)
	v_mfma_f32_16x16x32_bf16 v[96:99], v[12:15], v[40:43], v[92:95]
	s_nop 2
	v_mul_f32_e64 v92, v140, v120
	v_mul_f32_e64 v93, v141, v121
	v_pk_fma_f32 v[94:95], v[146:147], v[118:119], v[100:101]
	v_pk_fma_f32 v[92:93], v[142:143], v[116:117], v[92:93]
	s_nop 1
	v_mfma_f32_16x16x32_bf16 v[100:103], v[16:19], v[40:43], v[92:95]
	s_nop 2
	v_mul_f32_e64 v92, v154, v114
	v_mul_f32_e64 v93, v155, v115
	v_pk_mul_f32 v[114:115], v[152:153], v[114:115]
	v_pk_fma_f32 v[94:95], v[152:153], v[110:111], v[92:93] neg_lo:[0,0,1] neg_hi:[0,0,1]
	v_pk_fma_f32 v[92:93], v[148:149], v[108:109], v[104:105] neg_lo:[0,0,1] neg_hi:[0,0,1]
	v_pk_mul_f32 v[116:117], v[142:143], v[100:101]
	s_nop 0
	v_mfma_f32_16x16x32_bf16 v[104:107], v[4:7], v[40:43], v[92:95]
	s_nop 2
	v_mul_f32_e64 v92, v148, v112
	v_mul_f32_e64 v93, v149, v113
	v_pk_fma_f32 v[94:95], v[154:155], v[110:111], v[114:115]
	v_pk_fma_f32 v[92:93], v[150:151], v[108:109], v[92:93]
	v_cvt_pk_bf16_f32 v112, v100, v101
	v_cvt_pk_bf16_f32 v113, v102, v103
	v_mfma_f32_16x16x32_bf16 v[108:111], v[8:11], v[40:43], v[92:95]
	global_load_dwordx4 v[40:43], v[190:191], off
	v_lshl_add_u64 v[190:191], v[190:191], 0, v[206:207]
	v_mul_f32_e64 v100, v140, v100
	v_mul_f32_e64 v101, v141, v101
	s_nop 0
	v_cvt_pk_bf16_f32 v92, v96, v97
	v_cvt_pk_bf16_f32 v93, v98, v99
	v_cvt_pk_bf16_f32 v94, v104, v105
	v_cvt_pk_bf16_f32 v95, v106, v107
	s_nop 0
	v_cvt_pk_bf16_f32 v114, v108, v109
	v_cvt_pk_bf16_f32 v115, v110, v111
	v_mfma_f32_16x16x32_bf16 v[92:95], v[20:23], v[92:95], 0
	s_nop 0
	v_mfma_f32_16x16x32_bf16 v[92:95], v[24:27], v[112:115], v[92:95]
	v_mul_f32_e64 v112, v146, v102
	v_mul_f32_e64 v113, v147, v103
	v_pk_mul_f32 v[102:103], v[144:145], v[102:103]
	v_pk_fma_f32 v[114:115], v[144:145], v[98:99], v[112:113] neg_lo:[0,0,1] neg_hi:[0,0,1]
	v_pk_fma_f32 v[112:113], v[140:141], v[96:97], v[116:117] neg_lo:[0,0,1] neg_hi:[0,0,1]
	v_pk_fma_f32 v[98:99], v[146:147], v[98:99], v[102:103]
	v_pk_fma_f32 v[96:97], v[142:143], v[96:97], v[100:101]
	v_pk_mul_f32 v[116:117], v[150:151], v[108:109]
	s_waitcnt vmcnt(11)
	v_mfma_f32_16x16x32_bf16 v[112:115], v[12:15], v[36:39], v[112:115]
	v_mfma_f32_16x16x32_bf16 v[100:103], v[16:19], v[36:39], v[96:99]
	s_nop 2
	v_mul_f32_e64 v96, v154, v110
	v_mul_f32_e64 v97, v155, v111
	v_pk_mul_f32 v[110:111], v[152:153], v[110:111]
	v_pk_fma_f32 v[98:99], v[152:153], v[106:107], v[96:97] neg_lo:[0,0,1] neg_hi:[0,0,1]
	v_pk_fma_f32 v[96:97], v[148:149], v[104:105], v[116:117] neg_lo:[0,0,1] neg_hi:[0,0,1]
	v_pk_mul_f32 v[120:121], v[142:143], v[100:101]
	s_nop 0
	v_mfma_f32_16x16x32_bf16 v[116:119], v[4:7], v[36:39], v[96:99]
	s_nop 2
	v_mul_f32_e64 v96, v148, v108
	v_mul_f32_e64 v97, v149, v109
	v_pk_fma_f32 v[98:99], v[154:155], v[106:107], v[110:111]
	v_pk_fma_f32 v[96:97], v[150:151], v[104:105], v[96:97]
	v_cvt_pk_bf16_f32 v108, v100, v101
	v_cvt_pk_bf16_f32 v109, v102, v103
	v_mfma_f32_16x16x32_bf16 v[104:107], v[8:11], v[36:39], v[96:99]
	global_load_dwordx4 v[36:39], v[192:193], off
	v_lshl_add_u64 v[192:193], v[192:193], 0, v[206:207]
	v_mul_f32_e64 v100, v140, v100
	v_mul_f32_e64 v101, v141, v101
	v_pk_fma_f32 v[100:101], v[142:143], v[112:113], v[100:101]
	v_cvt_pk_bf16_f32 v96, v112, v113
	v_cvt_pk_bf16_f32 v97, v114, v115
	v_cvt_pk_bf16_f32 v98, v116, v117
	v_cvt_pk_bf16_f32 v99, v118, v119
	s_nop 0
	v_cvt_pk_bf16_f32 v110, v104, v105
	v_cvt_pk_bf16_f32 v111, v106, v107
	v_mfma_f32_16x16x32_bf16 v[96:99], v[20:23], v[96:99], 0
	s_nop 0
	v_mfma_f32_16x16x32_bf16 v[96:99], v[24:27], v[108:111], v[96:99]
	v_mul_f32_e64 v108, v146, v102
	v_mul_f32_e64 v109, v147, v103
	v_pk_mul_f32 v[102:103], v[144:145], v[102:103]
	v_pk_fma_f32 v[110:111], v[144:145], v[114:115], v[108:109] neg_lo:[0,0,1] neg_hi:[0,0,1]
	v_pk_fma_f32 v[102:103], v[146:147], v[114:115], v[102:103]
	v_pk_fma_f32 v[108:109], v[140:141], v[112:113], v[120:121] neg_lo:[0,0,1] neg_hi:[0,0,1]
	v_pk_mul_f32 v[120:121], v[150:151], v[104:105]
	s_waitcnt vmcnt(11)
	v_mfma_f32_16x16x32_bf16 v[112:115], v[16:19], v[56:59], v[100:103]
	s_nop 2
	v_mul_f32_e64 v100, v154, v106
	v_mul_f32_e64 v101, v155, v107
	v_mfma_f32_16x16x32_bf16 v[108:111], v[12:15], v[56:59], v[108:111]
	v_fma_f32 v102, v152, v118, -v100
	v_fma_f32 v103, v153, v119, -v101
	v_pk_fma_f32 v[100:101], v[148:149], v[116:117], v[120:121] neg_lo:[0,0,1] neg_hi:[0,0,1]
	v_pk_mul_f32 v[106:107], v[152:153], v[106:107]
	v_pk_mul_f32 v[124:125], v[142:143], v[112:113]
	v_mfma_f32_16x16x32_bf16 v[120:123], v[4:7], v[56:59], v[100:103]
	s_nop 2
	v_mul_f32_e64 v100, v148, v104
	v_mul_f32_e64 v101, v149, v105
	v_pk_fma_f32 v[102:103], v[154:155], v[118:119], v[106:107]
	v_pk_fma_f32 v[100:101], v[150:151], v[116:117], v[100:101]
	v_cvt_pk_bf16_f32 v116, v112, v113
	v_cvt_pk_bf16_f32 v117, v114, v115
	v_mfma_f32_16x16x32_bf16 v[104:107], v[8:11], v[56:59], v[100:103]
	global_load_dwordx4 v[56:59], v[194:195], off
	v_lshl_add_u64 v[194:195], v[194:195], 0, v[206:207]
	v_mul_f32_e64 v112, v140, v112
	v_mul_f32_e64 v113, v141, v113
	s_nop 0
	v_cvt_pk_bf16_f32 v100, v108, v109
	v_cvt_pk_bf16_f32 v101, v110, v111
	v_cvt_pk_bf16_f32 v102, v120, v121
	v_cvt_pk_bf16_f32 v103, v122, v123
	s_nop 0
	v_cvt_pk_bf16_f32 v118, v104, v105
	v_cvt_pk_bf16_f32 v119, v106, v107
	v_mfma_f32_16x16x32_bf16 v[100:103], v[20:23], v[100:103], 0
	s_nop 0
	v_mfma_f32_16x16x32_bf16 v[100:103], v[24:27], v[116:119], v[100:103]
	v_mul_f32_e64 v116, v146, v114
	v_mul_f32_e64 v117, v147, v115
	v_pk_fma_f32 v[118:119], v[144:145], v[110:111], v[116:117] neg_lo:[0,0,1] neg_hi:[0,0,1]
	v_pk_fma_f32 v[116:117], v[140:141], v[108:109], v[124:125] neg_lo:[0,0,1] neg_hi:[0,0,1]
	v_pk_mul_f32 v[124:125], v[144:145], v[114:115]
	v_pk_fma_f32 v[108:109], v[142:143], v[108:109], v[112:113]
	s_waitcnt vmcnt(11)
; DI unsigned pack2(float a, float b) { f32x2_t v = {a, b}; bf16x2_t r = __builtin_convertvector(v, bf16x2_t); return __builtin_bit_cast(unsigned, r); }
; DI f32x4 mfma16(bf16x8 a, bf16x8 b, f32x4 c) { return __builtin_amdgcn_mfma_f32_16x16x32_bf16(a, b, c, 0, 0, 0); }
; DI void s5_job(const PX& p, int l, int job, unsigned char* smem) {
;     ...
;           for (int s = 0; s < 8; s++) {
;             const int st = (blk + 1) * 8 + s;
;             const int t = dir ? Lseg - 1 - st : st;
;             unext[s] = *(const uint4*)(Zu + (size_t)(tokbase + t) * 768);
;           }
;         }
; #pragma unroll
;         for (int s = 0; s < 8; s++) {
;           const bf16x8 ub = u4_to_bf8(ucur[s]);
; #pragma unroll
;           for (int tt = 0; tt < 2; tt++) {
;             f32x4 cr, ci;
; #pragma unroll
;             for (int r = 0; r < 4; r++) {
;               cr[r] = lre[tt][r] * sre[tt][r] - lim[tt][r] * sim[tt][r];
;               ci[r] = lre[tt][r] * sim[tt][r] + lim[tt][r] * sre[tt][r];
;             }
;             sre[tt] = mfma16(Are[tt], ub, cr);
;             sim[tt] = mfma16(Aim[tt], ub, ci);
;           }
;           uint4 pr, pi;
;           pr.x = pack2(sre[0][0], sre[0][1]); pr.y = pack2(sre[0][2], sre[0][3]);
;           pr.z = pack2(sre[1][0], sre[1][1]); pr.w = pack2(sre[1][2], sre[1][3]);
;           pi.x = pack2(sim[0][0], sim[0][1]); pi.y = pack2(sim[0][2], sim[0][3]);
;           pi.z = pack2(sim[1][0], sim[1][1]); pi.w = pack2(sim[1][2], sim[1][3]);
;           f32x4 y = f32x4{0.f, 0.f, 0.f, 0.f};
;           y = mfma16(Cf[0], u4_to_bf8(pr), y);
;           y = mfma16(Cf[1], u4_to_bf8(pi), y);
;           yp[s] = y;
;         }
	v_mfma_f32_16x16x32_bf16 v[114:117], v[12:15], v[52:55], v[116:119]
	v_mul_f32_e64 v112, v154, v106
	v_mul_f32_e64 v113, v155, v107
	v_pk_fma_f32 v[110:111], v[146:147], v[110:111], v[124:125]
	v_pk_fma_f32 v[126:127], v[152:153], v[122:123], v[112:113] neg_lo:[0,0,1] neg_hi:[0,0,1]
	v_pk_mul_f32 v[118:119], v[150:151], v[104:105]
	v_pk_mul_f32 v[106:107], v[152:153], v[106:107]
	v_pk_fma_f32 v[124:125], v[148:149], v[120:121], v[118:119] neg_lo:[0,0,1] neg_hi:[0,0,1]
	v_pk_mul_f32 v[104:105], v[148:149], v[104:105]
	v_pk_fma_f32 v[106:107], v[154:155], v[122:123], v[106:107]
	v_mfma_f32_16x16x32_bf16 v[124:127], v[4:7], v[52:55], v[124:127]
	v_fma_f32 v104, v150, v120, v104
	v_fma_f32 v105, v151, v121, v105
	v_mfma_f32_16x16x32_bf16 v[108:111], v[16:19], v[52:55], v[108:111]
	s_nop 0
	v_mfma_f32_16x16x32_bf16 v[118:121], v[8:11], v[52:55], v[104:107]
	global_load_dwordx4 v[52:55], v[196:197], off
	v_lshl_add_u64 v[196:197], v[196:197], 0, v[206:207]
	s_nop 2
	v_cvt_pk_bf16_f32 v104, v114, v115
	v_cvt_pk_bf16_f32 v105, v116, v117
	v_cvt_pk_bf16_f32 v106, v124, v125
	v_cvt_pk_bf16_f32 v107, v126, v127
	v_cvt_pk_bf16_f32 v128, v108, v109
	v_cvt_pk_bf16_f32 v129, v110, v111
	v_mfma_f32_16x16x32_bf16 v[104:107], v[20:23], v[104:107], 0
	v_cvt_pk_bf16_f32 v130, v118, v119
	v_cvt_pk_bf16_f32 v131, v120, v121
	v_pk_mul_f32 v[122:123], v[142:143], v[108:109]
	v_pk_mul_f32 v[112:113], v[146:147], v[110:111]
	v_mfma_f32_16x16x32_bf16 v[104:107], v[24:27], v[128:131], v[104:107]
	v_fma_f32 v128, v140, v114, -v122
	v_fma_f32 v129, v141, v115, -v123
	v_pk_mul_f32 v[122:123], v[144:145], v[110:111]
	v_pk_mul_f32 v[108:109], v[140:141], v[108:109]
	v_pk_fma_f32 v[130:131], v[144:145], v[116:117], v[112:113] neg_lo:[0,0,1] neg_hi:[0,0,1]
	v_pk_fma_f32 v[116:117], v[146:147], v[116:117], v[122:123]
	v_pk_fma_f32 v[114:115], v[142:143], v[114:115], v[108:109]
	v_pk_mul_f32 v[108:109], v[154:155], v[120:121]
	v_pk_mul_f32 v[122:123], v[150:151], v[118:119]
	s_waitcnt vmcnt(11)
	v_mfma_f32_16x16x32_bf16 v[110:113], v[12:15], v[72:75], v[128:131]
	v_mul_f32_e64 v118, v148, v118
	v_mul_f32_e64 v119, v149, v119
	s_nop 0
	v_pk_fma_f32 v[130:131], v[152:153], v[126:127], v[108:109] neg_lo:[0,0,1] neg_hi:[0,0,1]
	v_pk_fma_f32 v[128:129], v[148:149], v[124:125], v[122:123] neg_lo:[0,0,1] neg_hi:[0,0,1]
	v_pk_mul_f32 v[108:109], v[152:153], v[120:121]
	v_pk_fma_f32 v[124:125], v[150:151], v[124:125], v[118:119]
	v_mfma_f32_16x16x32_bf16 v[120:123], v[4:7], v[72:75], v[128:131]
	v_fma_f32 v126, v154, v126, v108
	v_fma_f32 v127, v155, v127, v109
	v_mfma_f32_16x16x32_bf16 v[114:117], v[16:19], v[72:75], v[114:117]
	s_nop 0
	v_mfma_f32_16x16x32_bf16 v[128:131], v[8:11], v[72:75], v[124:127]
	global_load_dwordx4 v[72:75], v[198:199], off
	v_lshl_add_u64 v[198:199], v[198:199], 0, v[206:207]
	s_nop 2
	v_cvt_pk_bf16_f32 v124, v110, v111
	v_cvt_pk_bf16_f32 v125, v112, v113
	v_cvt_pk_bf16_f32 v126, v120, v121
	v_cvt_pk_bf16_f32 v127, v122, v123
	v_cvt_pk_bf16_f32 v132, v114, v115
	v_cvt_pk_bf16_f32 v133, v116, v117
	v_mfma_f32_16x16x32_bf16 v[124:127], v[20:23], v[124:127], 0
	v_cvt_pk_bf16_f32 v134, v128, v129
	v_cvt_pk_bf16_f32 v135, v130, v131
	v_pk_mul_f32 v[108:109], v[146:147], v[116:117]
	v_pk_mul_f32 v[118:119], v[142:143], v[114:115]
	v_mfma_f32_16x16x32_bf16 v[124:127], v[24:27], v[132:135], v[124:127]
	v_fma_f32 v134, v144, v112, -v108
	v_fma_f32 v135, v145, v113, -v109
	v_pk_mul_f32 v[108:109], v[144:145], v[116:117]
	v_pk_mul_f32 v[114:115], v[140:141], v[114:115]
	v_pk_fma_f32 v[132:133], v[140:141], v[110:111], v[118:119] neg_lo:[0,0,1] neg_hi:[0,0,1]
	v_pk_fma_f32 v[112:113], v[146:147], v[112:113], v[108:109]
	v_pk_fma_f32 v[110:111], v[142:143], v[110:111], v[114:115]
	s_waitcnt vmcnt(11)
; DI unsigned pack2(float a, float b) { f32x2_t v = {a, b}; bf16x2_t r = __builtin_convertvector(v, bf16x2_t); return __builtin_bit_cast(unsigned, r); }
; DI f32x4 mfma16(bf16x8 a, bf16x8 b, f32x4 c) { return __builtin_amdgcn_mfma_f32_16x16x32_bf16(a, b, c, 0, 0, 0); }
; DI void s5_job(const PX& p, int l, int job, unsigned char* smem) {
;     ...
;           for (int s = 0; s < 8; s++) {
;             const int st = (blk + 1) * 8 + s;
;             const int t = dir ? Lseg - 1 - st : st;
;             unext[s] = *(const uint4*)(Zu + (size_t)(tokbase + t) * 768);
;           }
;         }
; #pragma unroll
;         for (int s = 0; s < 8; s++) {
;           const bf16x8 ub = u4_to_bf8(ucur[s]);
; #pragma unroll
;           for (int tt = 0; tt < 2; tt++) {
;             f32x4 cr, ci;
; #pragma unroll
;             for (int r = 0; r < 4; r++) {
;               cr[r] = lre[tt][r] * sre[tt][r] - lim[tt][r] * sim[tt][r];
;               ci[r] = lre[tt][r] * sim[tt][r] + lim[tt][r] * sre[tt][r];
;             }
;             sre[tt] = mfma16(Are[tt], ub, cr);
;             sim[tt] = mfma16(Aim[tt], ub, ci);
;           }
;           uint4 pr, pi;
;           pr.x = pack2(sre[0][0], sre[0][1]); pr.y = pack2(sre[0][2], sre[0][3]);
;           pr.z = pack2(sre[1][0], sre[1][1]); pr.w = pack2(sre[1][2], sre[1][3]);
;           pi.x = pack2(sim[0][0], sim[0][1]); pi.y = pack2(sim[0][2], sim[0][3]);
;           pi.z = pack2(sim[1][0], sim[1][1]); pi.w = pack2(sim[1][2], sim[1][3]);
;           f32x4 y = f32x4{0.f, 0.f, 0.f, 0.f};
;           y = mfma16(Cf[0], u4_to_bf8(pr), y);
;           y = mfma16(Cf[1], u4_to_bf8(pi), y);
;           yp[s] = y;
;         }
;         if (hf == 1) {
; #pragma unroll
;           for (int s = 0; s < 8; s++)
; #pragma unroll
;             for (int r = 0; r < 4; r++) exb[(s * 4 + r) * 64] = yp[s][r];
;         }
	v_mfma_f32_16x16x32_bf16 v[116:119], v[12:15], v[68:71], v[132:135]
	v_mfma_f32_16x16x32_bf16 v[108:111], v[16:19], v[68:71], v[110:113]
	s_nop 1
	v_mul_f32_e64 v132, v150, v128
	v_mul_f32_e64 v133, v151, v129
	v_pk_mul_f32 v[128:129], v[148:149], v[128:129]
	v_pk_mul_f32 v[112:113], v[154:155], v[130:131]
	v_pk_mul_f32 v[130:131], v[152:153], v[130:131]
	v_pk_fma_f32 v[114:115], v[152:153], v[122:123], v[112:113] neg_lo:[0,0,1] neg_hi:[0,0,1]
	v_pk_fma_f32 v[112:113], v[148:149], v[120:121], v[132:133] neg_lo:[0,0,1] neg_hi:[0,0,1]
	v_pk_fma_f32 v[122:123], v[154:155], v[122:123], v[130:131]
	v_pk_fma_f32 v[120:121], v[150:151], v[120:121], v[128:129]
	v_mfma_f32_16x16x32_bf16 v[112:115], v[4:7], v[68:71], v[112:115]
	v_cvt_pk_bf16_f32 v128, v116, v117
	v_cvt_pk_bf16_f32 v129, v118, v119
	v_cvt_pk_bf16_f32 v132, v108, v109
	v_mfma_f32_16x16x32_bf16 v[120:123], v[8:11], v[68:71], v[120:123]
	global_load_dwordx4 v[68:71], v[200:201], off
	v_lshl_add_u64 v[200:201], v[200:201], 0, v[206:207]
	v_cvt_pk_bf16_f32 v133, v110, v111
	s_nop 2
	v_cvt_pk_bf16_f32 v130, v112, v113
	v_cvt_pk_bf16_f32 v131, v114, v115
	v_pk_mul_f32 v[136:137], v[142:143], v[108:109]
	v_pk_mul_f32 v[108:109], v[140:141], v[108:109]
	v_mfma_f32_16x16x32_bf16 v[128:131], v[20:23], v[128:131], 0
	v_cvt_pk_bf16_f32 v134, v120, v121
	v_cvt_pk_bf16_f32 v135, v122, v123
	v_pk_fma_f32 v[108:109], v[142:143], v[116:117], v[108:109]
	s_nop 0
	v_mfma_f32_16x16x32_bf16 v[128:131], v[24:27], v[132:135], v[128:131]
	v_mul_f32_e64 v132, v146, v110
	v_mul_f32_e64 v133, v147, v111
	v_pk_mul_f32 v[110:111], v[144:145], v[110:111]
	v_pk_fma_f32 v[134:135], v[144:145], v[118:119], v[132:133] neg_lo:[0,0,1] neg_hi:[0,0,1]
	v_pk_fma_f32 v[132:133], v[140:141], v[116:117], v[136:137] neg_lo:[0,0,1] neg_hi:[0,0,1]
	v_pk_mul_f32 v[116:117], v[154:155], v[122:123]
	v_pk_fma_f32 v[110:111], v[146:147], v[118:119], v[110:111]
	s_waitcnt vmcnt(11)
	v_mfma_f32_16x16x32_bf16 v[136:139], v[12:15], v[88:91], v[132:135]
	v_fma_f32 v118, v152, v114, -v116
	v_fma_f32 v119, v153, v115, -v117
	v_pk_mul_f32 v[122:123], v[152:153], v[122:123]
	v_pk_mul_f32 v[132:133], v[150:151], v[120:121]
	v_pk_fma_f32 v[114:115], v[154:155], v[114:115], v[122:123]
	v_pk_fma_f32 v[116:117], v[148:149], v[112:113], v[132:133] neg_lo:[0,0,1] neg_hi:[0,0,1]
	v_mfma_f32_16x16x32_bf16 v[108:111], v[16:19], v[88:91], v[108:111]
	s_nop 0
	v_mfma_f32_16x16x32_bf16 v[164:167], v[4:7], v[88:91], v[116:119]
	s_nop 2
	v_mul_f32_e64 v116, v148, v120
	v_mul_f32_e64 v117, v149, v121
	s_nop 0
	v_cvt_pk_bf16_f32 v120, v108, v109
	v_pk_fma_f32 v[112:113], v[150:151], v[112:113], v[116:117]
	v_cvt_pk_bf16_f32 v116, v136, v137
	v_cvt_pk_bf16_f32 v117, v138, v139
	v_mfma_f32_16x16x32_bf16 v[112:115], v[8:11], v[88:91], v[112:115]
	global_load_dwordx4 v[88:91], v[202:203], off
	v_lshl_add_u64 v[202:203], v[202:203], 0, v[206:207]
	v_cvt_pk_bf16_f32 v118, v164, v165
	v_cvt_pk_bf16_f32 v119, v166, v167
	v_cvt_pk_bf16_f32 v121, v110, v111
	s_nop 0
	v_mfma_f32_16x16x32_bf16 v[116:119], v[20:23], v[116:119], 0
	s_nop 2
	v_cvt_pk_bf16_f32 v122, v112, v113
	v_cvt_pk_bf16_f32 v123, v114, v115
	s_nop 1
	v_mfma_f32_16x16x32_bf16 v[132:135], v[24:27], v[120:123], v[116:119]
	v_mul_f32_e64 v120, v142, v108
	v_mul_f32_e64 v121, v143, v109
	v_pk_mul_f32 v[108:109], v[140:141], v[108:109]
	v_pk_mul_f32 v[116:117], v[146:147], v[110:111]
	v_pk_mul_f32 v[110:111], v[144:145], v[110:111]
	v_pk_fma_f32 v[108:109], v[142:143], v[136:137], v[108:109]
	v_pk_fma_f32 v[110:111], v[146:147], v[138:139], v[110:111]
	v_pk_fma_f32 v[118:119], v[144:145], v[138:139], v[116:117] neg_lo:[0,0,1] neg_hi:[0,0,1]
	v_pk_fma_f32 v[116:117], v[140:141], v[136:137], v[120:121] neg_lo:[0,0,1] neg_hi:[0,0,1]
	s_waitcnt vmcnt(11)
	v_mfma_f32_16x16x32_bf16 v[120:123], v[16:19], v[84:87], v[108:111]
	v_mul_f32_e64 v136, v150, v112
	v_mul_f32_e64 v137, v151, v113
	v_pk_mul_f32 v[112:113], v[148:149], v[112:113]
	v_pk_mul_f32 v[108:109], v[154:155], v[114:115]
	v_mfma_f32_16x16x32_bf16 v[116:119], v[12:15], v[84:87], v[116:119]
	v_fma_f32 v110, v152, v166, -v108
	v_fma_f32 v111, v153, v167, -v109
	v_pk_fma_f32 v[108:109], v[148:149], v[164:165], v[136:137] neg_lo:[0,0,1] neg_hi:[0,0,1]
	v_pk_mul_f32 v[114:115], v[152:153], v[114:115]
	v_pk_fma_f32 v[112:113], v[150:151], v[164:165], v[112:113]
	v_mfma_f32_16x16x32_bf16 v[108:111], v[4:7], v[84:87], v[108:111]
	v_fma_f32 v114, v154, v166, v114
	v_fma_f32 v115, v155, v167, v115
	v_cvt_pk_bf16_f32 v136, v116, v117
	v_cvt_pk_bf16_f32 v137, v118, v119
	v_mfma_f32_16x16x32_bf16 v[112:115], v[8:11], v[84:87], v[112:115]
	global_load_dwordx4 v[84:87], v[204:205], off
	v_lshl_add_u64 v[204:205], v[204:205], 0, v[206:207]
	v_cvt_pk_bf16_f32 v164, v120, v121
	s_nop 1
	v_cvt_pk_bf16_f32 v138, v108, v109
	v_cvt_pk_bf16_f32 v139, v110, v111
	v_cvt_pk_bf16_f32 v165, v122, v123
	s_nop 0
	v_mfma_f32_16x16x32_bf16 v[136:139], v[20:23], v[136:139], 0
	v_cvt_pk_bf16_f32 v166, v112, v113
	v_cvt_pk_bf16_f32 v167, v114, v115
	s_nop 1
	v_mfma_f32_16x16x32_bf16 v[136:139], v[24:27], v[164:167], v[136:139]
	v_mad_u32_u24 v163, v211, 12, v0
	s_and_saveexec_b64 s[16:17], s[8:9]
	s_cbranch_execz .Ls5x_w0
	ds_write_b128 v163, v[92:95]
	ds_write_b128 v163, v[96:99] offset:1024
	ds_write_b128 v163, v[100:103] offset:2048
	ds_write_b128 v163, v[104:107] offset:3072
